# pipelined GEMM K-loops: workgroups 0..255 run their K-loops at wave priority 1 and workgroups 256..511 at 0, so the two workgroups sharing a CU fall out of phase (one computes while the other waits on
# speedup vs baseline: 1.0149x; 1.0070x over previous
; template <int EPI, int MI>
; DI void gemm_tile(const GemmDesc& g, int tm, int tn, char* smem) {
;     ...
;   const int tid = get_tid(), lane = tid & 63, wave = tid >> 6, r = lane & 31, hh = lane >> 5;
;   const int wm = wave >> 1, wn = wave & 1;
;   const int m0 = tm * BM, n0 = tn * 128;
;   const int nk = g.K >> 6;
;   f32x16 acc[MI][2];
; #pragma unroll
;   for (int a = 0; a < MI; ++a)
; #pragma unroll
;     for (int b = 0; b < 2; ++b)
; #pragma unroll
;       for (int i = 0; i < 16; ++i) acc[a][b][i] = 0.f;
;   const int srow = tid >> 3;
;   const int schunk = (tid & 7) ^ ((srow & 7) ^ ((srow >> 3) & 3));
;     ...
;   const int rowA = wm * (32 * MI) + r, rowB = wn * 64 + r;
;   const int hk = hh ^ ((r & 7) ^ ((r >> 3) & 3));
;     ...
;   G_GLDS(0, 0);
;   asm volatile("s_waitcnt vmcnt(0)" ::: "memory");
;   __syncthreads();
; template <int EPI, int MI>
; DI void gemm_phase(const GemmDesc& g, char* smem, int vb, int nvb) {
;     ...
;   for (int q = start; q < local; q += step) {
;     const int mg = q / per;
;     const int rem = q - mg * per;
;     const int tn = rem / PM;
;     const int tm = mbase + mg * PM + (rem - tn * PM);
.LBB0_202:
	s_abs_i32 s1, s5
	v_readlane_b32 s15, v219, 45
	s_mul_hi_u32 s15, s1, s15
	v_readlane_b32 s18, v219, 44
	s_mul_i32 s16, s15, s18
	s_sub_i32 s1, s1, s16
	s_ashr_i32 s0, s5, 31
	s_add_i32 s16, s15, 1
	s_sub_i32 s17, s1, s18
	s_cmp_ge_u32 s1, s18
	s_cselect_b32 s15, s16, s15
	s_cselect_b32 s1, s17, s1
	s_add_i32 s16, s15, 1
	s_cmp_ge_u32 s1, s18
	s_cselect_b32 s1, s16, s15
	s_xor_b32 s1, s1, s0
	s_sub_i32 s15, s1, s0
	s_mul_i32 s16, s15, s18
	s_sub_i32 s16, s5, s16
	s_abs_i32 s18, s16
	v_readlane_b32 s19, v219, 46
	s_mul_hi_u32 s19, s18, s19
	v_readlane_b32 s42, v218, 32
	s_mul_i32 s38, s19, s42
	s_sub_i32 s18, s18, s38
	s_ashr_i32 s17, s16, 31
	s_add_i32 s38, s19, 1
	s_sub_i32 s39, s18, s42
	s_cmp_ge_u32 s18, s42
	s_cselect_b32 s19, s38, s19
	s_cselect_b32 s18, s39, s18
	s_add_i32 s38, s19, 1
	s_cmp_ge_u32 s18, s42
	s_cselect_b32 s18, s38, s19
	s_xor_b32 s18, s18, s17
	s_sub_i32 s39, s18, s17
	s_sub_i32 s15, s15, s39
	v_mov_b32_e32 v4, v132
	s_mul_i32 s15, s15, s42
	s_add_i32 s16, s16, s54
	s_add_i32 s38, s16, s15
	v_ashrrev_i32_e32 v97, 3, v4
	v_ashrrev_i32_e32 v120, 7, v4
	v_bfe_u32 v0, v4, 6, 2
	v_xor_b32_e32 v1, v97, v4
	s_mulk_i32 s38, 0xc0
	v_and_b32_e32 v121, 31, v4
	v_bitop3_b32 v2, v1, v0, 7 bitop3:0x6c
	v_mul_lo_u32 v0, v120, s6
	v_and_b32_e32 v115, 7, v4
	v_or_b32_e32 v5, v0, v121
	v_lshrrev_b32_e32 v0, 3, v4
	s_waitcnt vmcnt(10)
	v_add_u32_e32 v98, s38, v97
	v_bfe_u32 v122, v4, 5, 1
	v_bitop3_b32 v0, v0, v115, 3 bitop3:0x6c
	v_ashrrev_i32_e32 v99, 31, v98
	v_xor_b32_e32 v6, v0, v122
	v_lshlrev_b64 v[0:1], 11, v[98:99]
	v_readlane_b32 s42, v223, 59
	v_lshlrev_b32_e32 v99, 4, v4
	v_readlane_b32 s43, v223, 60
	v_lshlrev_b32_e32 v100, 4, v2
	v_lshl_add_u32 v2, s39, 7, v97
	v_add_u32_e32 v124, 0, v99
	v_lshl_add_u64 v[0:1], s[42:43], 0, v[0:1]
	v_mov_b32_e32 v101, v96
	v_ashrrev_i32_e32 v3, 31, v2
	v_readfirstlane_b32 s15, v124
	v_add_u32_e32 v125, 0x1000, v124
	v_lshl_add_u64 v[0:1], v[0:1], 0, v[100:101]
	v_lshlrev_b64 v[2:3], 11, v[2:3]
	s_mov_b32 m0, s15
	s_mov_b64 s[42:43], 0x10000
	v_readfirstlane_b32 s15, v125
	v_add_u32_e32 v126, 0x2000, v124
	s_waitcnt vmcnt(9)
	v_lshl_add_u64 v[102:103], s[70:71], 0, v[2:3]
	global_load_lds_dwordx4 v[0:1], off
	v_lshl_add_u64 v[2:3], v[0:1], 0, s[42:43]
	s_mov_b32 m0, s15
	s_mov_b64 s[44:45], 0x20000
	v_readfirstlane_b32 s15, v126
	v_add_u32_e32 v127, 0x3000, v124
	global_load_lds_dwordx4 v[2:3], off
	v_lshl_add_u64 v[2:3], v[0:1], 0, s[44:45]
	s_mov_b32 m0, s15
	s_mov_b64 s[46:47], 0x30000
	v_readfirstlane_b32 s15, v127
	v_add_u32_e32 v128, 0x4000, v124
	global_load_lds_dwordx4 v[2:3], off
	v_lshl_add_u64 v[2:3], v[0:1], 0, s[46:47]
	s_mov_b32 m0, s15
	s_mov_b64 s[52:53], 0x40000
	v_readfirstlane_b32 s15, v128
	v_add_u32_e32 v129, 0x5000, v124
	global_load_lds_dwordx4 v[2:3], off
	v_lshl_add_u64 v[2:3], v[0:1], 0, s[52:53]
	s_mov_b32 m0, s15
	s_mov_b64 s[52:53], 0x50000
	v_readfirstlane_b32 s15, v129
	v_add_u32_e32 v130, 0xc000, v124
	global_load_lds_dwordx4 v[2:3], off
	v_lshl_add_u64 v[0:1], v[0:1], 0, s[52:53]
	s_mov_b32 m0, s15
	v_readfirstlane_b32 s15, v130
	v_add_u32_e32 v131, 0xd000, v124
	global_load_lds_dwordx4 v[0:1], off
	v_lshl_add_u64 v[0:1], v[102:103], 0, v[100:101]
	s_mov_b32 m0, s15
	v_readfirstlane_b32 s15, v131
	v_add_u32_e32 v153, 0xe000, v124
	global_load_lds_dwordx4 v[0:1], off
	v_lshl_add_u64 v[2:3], v[0:1], 0, s[42:43]
	s_mov_b32 m0, s15
	v_readfirstlane_b32 s15, v153
	v_add_u32_e32 v154, 0xf000, v124
	global_load_lds_dwordx4 v[2:3], off
	v_lshl_add_u64 v[2:3], v[0:1], 0, s[44:45]
	s_mov_b32 m0, s15
	v_readfirstlane_b32 s15, v154
	global_load_lds_dwordx4 v[2:3], off
	v_lshl_add_u64 v[0:1], v[0:1], 0, s[46:47]
	s_mov_b32 m0, s15
	s_mul_i32 s0, s0, 43
	global_load_lds_dwordx4 v[0:1], off
	s_add_i32 s17, s17, s0
	s_sub_i32 s0, s17, s18
	s_mul_i32 s1, s1, 43
	s_sub_i32 s0, s0, s1
	v_readlane_b32 s1, v218, 33
	v_bfe_u32 v123, v4, 6, 1
	v_lshlrev_b32_e32 v0, 7, v121
	s_mul_i32 s0, s1, s0
	v_lshl_or_b32 v0, v123, 13, v0
	s_add_i32 s0, s0, s4
	v_add_u32_e32 v156, 0, v0
	v_add_u32_e32 v158, s10, v0
	v_add_u32_e32 v0, s0, v97
	v_ashrrev_i32_e32 v1, 31, v0
	s_waitcnt vmcnt(0)
	v_lshlrev_b64 v[0:1], 11, v[0:1]
	v_lshlrev_b32_e32 v157, 4, v6
	v_lshl_add_u64 v[104:105], s[70:71], 0, v[0:1]
	v_mov_b32_e32 v0, 0
	v_lshl_add_u32 v155, v5, 7, 0
	s_mov_b32 s15, 0
	v_mov_b32_e32 v1, v0
	v_mov_b32_e32 v2, v0
	v_mov_b32_e32 v3, v0
	v_mov_b32_e32 v4, v0
	v_mov_b32_e32 v5, v0
	v_mov_b32_e32 v6, v0
	v_mov_b32_e32 v7, v0
	v_mov_b32_e32 v8, v0
	v_mov_b32_e32 v9, v0
	v_mov_b32_e32 v10, v0
	v_mov_b32_e32 v11, v0
	v_mov_b32_e32 v12, v0
	v_mov_b32_e32 v13, v0
	v_mov_b32_e32 v14, v0
	v_mov_b32_e32 v15, v0
	v_mov_b32_e32 v16, v0
	v_mov_b32_e32 v17, v0
	v_mov_b32_e32 v18, v0
	v_mov_b32_e32 v19, v0
	v_mov_b32_e32 v20, v0
	v_mov_b32_e32 v21, v0
	v_mov_b32_e32 v22, v0
	v_mov_b32_e32 v23, v0
	v_mov_b32_e32 v24, v0
	v_mov_b32_e32 v25, v0
	v_mov_b32_e32 v26, v0
	v_mov_b32_e32 v27, v0
	v_mov_b32_e32 v28, v0
	v_mov_b32_e32 v29, v0
	v_mov_b32_e32 v30, v0
	v_mov_b32_e32 v31, v0
	v_mov_b32_e32 v32, v0
	v_mov_b32_e32 v33, v0
	v_mov_b32_e32 v34, v0
	v_mov_b32_e32 v35, v0
	v_mov_b32_e32 v36, v0
	v_mov_b32_e32 v37, v0
	v_mov_b32_e32 v38, v0
	v_mov_b32_e32 v39, v0
	v_mov_b32_e32 v40, v0
	v_mov_b32_e32 v41, v0
	v_mov_b32_e32 v42, v0
	v_mov_b32_e32 v43, v0
	v_mov_b32_e32 v44, v0
	v_mov_b32_e32 v45, v0
	v_mov_b32_e32 v46, v0
	v_mov_b32_e32 v47, v0
	v_mov_b32_e32 v48, v0
	s_waitcnt vmcnt(0)
	v_mov_b32_e32 v49, v0
	v_mov_b32_e32 v50, v0
	v_mov_b32_e32 v51, v0
	v_mov_b32_e32 v52, v0
	v_mov_b32_e32 v53, v0
	v_mov_b32_e32 v54, v0
	v_mov_b32_e32 v55, v0
	v_mov_b32_e32 v56, v0
	v_mov_b32_e32 v57, v0
	v_mov_b32_e32 v58, v0
	v_mov_b32_e32 v59, v0
	v_mov_b32_e32 v60, v0
	v_mov_b32_e32 v61, v0
	v_mov_b32_e32 v62, v0
	v_mov_b32_e32 v63, v0
	v_mov_b32_e32 v64, v0
	v_mov_b32_e32 v65, v0
	v_mov_b32_e32 v66, v0
	v_mov_b32_e32 v67, v0
	v_mov_b32_e32 v68, v0
	v_mov_b32_e32 v69, v0
	v_mov_b32_e32 v70, v0
	v_mov_b32_e32 v71, v0
	v_mov_b32_e32 v72, v0
	v_mov_b32_e32 v73, v0
	v_mov_b32_e32 v74, v0
	v_mov_b32_e32 v75, v0
	v_mov_b32_e32 v76, v0
	v_mov_b32_e32 v77, v0
	v_mov_b32_e32 v78, v0
	v_mov_b32_e32 v79, v0
	v_mov_b32_e32 v80, v0
	v_mov_b32_e32 v81, v0
	v_mov_b32_e32 v82, v0
	v_mov_b32_e32 v83, v0
	v_mov_b32_e32 v84, v0
	v_mov_b32_e32 v85, v0
	v_mov_b32_e32 v86, v0
	v_mov_b32_e32 v87, v0
	v_mov_b32_e32 v88, v0
	v_mov_b32_e32 v89, v0
	v_mov_b32_e32 v90, v0
	v_mov_b32_e32 v91, v0
	v_mov_b32_e32 v92, v0
	v_mov_b32_e32 v93, v0
	v_mov_b32_e32 v94, v0
	v_mov_b32_e32 v95, v0
	v_xor_b32_e32 v159, 32, v157
	v_xor_b32_e32 v160, 64, v157
	v_xor_b32_e32 v161, 0x60, v157
	s_mov_b64 s[18:19], 0x80
	s_mov_b64 s[42:43], 0x10080
	v_readlane_b32 s100, v218, 17
	s_nop 3
	s_cmp_lt_i32 s100, 0
	s_cbranch_scc0 .Lga_noprio
	s_setprio 1
; template <int EPI, int MI>
; DI void gemm_tile(const GemmDesc& g, int tm, int tn, char* smem) {
;     ...
;   const int rowA = wm * (32 * MI) + r, rowB = wn * 64 + r;
;   const int hk = hh ^ ((r & 7) ^ ((r >> 3) & 3));
;     ...
;   G_GLDS(0, 0);
;   asm volatile("s_waitcnt vmcnt(0)" ::: "memory");
;   __syncthreads();
.Lga_noprio:
	v_add_u32_e32 v162, v155, v157
	v_add_u32_e32 v163, v155, v159
	v_add_u32_e32 v164, v155, v160
	v_add_u32_e32 v165, v155, v161
	v_add_u32_e32 v166, v156, v157
	v_add_u32_e32 v167, v156, v159
	v_add_u32_e32 v168, v156, v160
	v_add_u32_e32 v169, v156, v161
	v_add_u32_e32 v170, v158, v157
	v_add_u32_e32 v171, v158, v159
	v_add_u32_e32 v172, v158, v160
	v_add_u32_e32 v173, v158, v161
	v_lshl_add_u64 v[174:175], v[104:105], 0, v[100:101]
	v_lshl_add_u64 v[176:177], v[102:103], 0, v[100:101]
	v_readfirstlane_b32 s100, v124
	s_waitcnt vmcnt(0) lgkmcnt(0)
	s_barrier
	s_add_u32 m0, s100, 0x6000
	v_lshl_add_u64 v[106:107], v[174:175], 0, s[96:97]
	global_load_lds_dwordx4 v[106:107], off
	s_add_u32 m0, s100, 0x7000
	v_lshl_add_u64 v[106:107], v[174:175], 0, s[50:51]
	global_load_lds_dwordx4 v[106:107], off
	ds_read_b128 v[236:239], v166 offset:49152
	ds_read_b128 v[240:243], v166 offset:53248
	ds_read_b128 v[224:227], v162
	ds_read_b128 v[228:231], v162 offset:4096
	s_mov_b32 s15, 0

; template <int EPI, int MI>
; DI void gemm_tile(const GemmDesc& g, int tm, int tn, char* smem) {
;     ...
;   for (int kt = 0; kt < nk; kt += 2) {
;     if (kt + 1 < nk) G_GLDS(kt + 1, 1);
;     G_COMPUTE(0);
;     asm volatile("s_waitcnt vmcnt(0)" ::: "memory");
;     __syncthreads();
;     if (kt + 1 < nk) {
;       if (kt + 2 < nk) G_GLDS(kt + 2, 0);
;       G_COMPUTE(1);
;       asm volatile("s_waitcnt vmcnt(0)" ::: "memory");
;       __syncthreads();
;     }
;   }
.Lga_last:
	ds_read_b128 v[232:235], v162 offset:32768
	s_waitcnt lgkmcnt(2)
	v_mfma_f32_32x32x16_bf16 v[80:95], v[224:227], v[236:239], v[80:95]
	v_mfma_f32_32x32x16_bf16 v[64:79], v[224:227], v[240:243], v[64:79]
	ds_read_b128 v[244:247], v171
	ds_read_b128 v[248:251], v171 offset:4096
	ds_read_b128 v[224:227], v163 offset:24576
	s_waitcnt lgkmcnt(4)
	v_mfma_f32_32x32x16_bf16 v[48:63], v[228:231], v[236:239], v[48:63]
	v_mfma_f32_32x32x16_bf16 v[32:47], v[228:231], v[240:243], v[32:47]
	ds_read_b128 v[228:231], v163 offset:28672
	s_waitcnt lgkmcnt(4)
	v_mfma_f32_32x32x16_bf16 v[16:31], v[232:235], v[236:239], v[16:31]
	v_mfma_f32_32x32x16_bf16 v[0:15], v[232:235], v[240:243], v[0:15]
	ds_read_b128 v[232:235], v163 offset:32768
	s_waitcnt lgkmcnt(2)
	v_mfma_f32_32x32x16_bf16 v[80:95], v[224:227], v[244:247], v[80:95]
	v_mfma_f32_32x32x16_bf16 v[64:79], v[224:227], v[248:251], v[64:79]
	ds_read_b128 v[236:239], v172
	ds_read_b128 v[240:243], v172 offset:4096
	ds_read_b128 v[224:227], v164 offset:24576
	s_waitcnt lgkmcnt(4)
	v_mfma_f32_32x32x16_bf16 v[48:63], v[228:231], v[244:247], v[48:63]
	v_mfma_f32_32x32x16_bf16 v[32:47], v[228:231], v[248:251], v[32:47]
	ds_read_b128 v[228:231], v164 offset:28672
	s_waitcnt lgkmcnt(4)
	v_mfma_f32_32x32x16_bf16 v[16:31], v[232:235], v[244:247], v[16:31]
	v_mfma_f32_32x32x16_bf16 v[0:15], v[232:235], v[248:251], v[0:15]
	ds_read_b128 v[232:235], v164 offset:32768
	s_waitcnt lgkmcnt(2)
	v_mfma_f32_32x32x16_bf16 v[80:95], v[224:227], v[236:239], v[80:95]
	v_mfma_f32_32x32x16_bf16 v[64:79], v[224:227], v[240:243], v[64:79]
	ds_read_b128 v[244:247], v173
	ds_read_b128 v[248:251], v173 offset:4096
	ds_read_b128 v[224:227], v165 offset:24576
	s_waitcnt lgkmcnt(4)
	v_mfma_f32_32x32x16_bf16 v[48:63], v[228:231], v[236:239], v[48:63]
	v_mfma_f32_32x32x16_bf16 v[32:47], v[228:231], v[240:243], v[32:47]
	ds_read_b128 v[228:231], v165 offset:28672
	s_waitcnt lgkmcnt(4)
	v_mfma_f32_32x32x16_bf16 v[16:31], v[232:235], v[236:239], v[16:31]
	v_mfma_f32_32x32x16_bf16 v[0:15], v[232:235], v[240:243], v[0:15]
	ds_read_b128 v[232:235], v165 offset:32768
	s_waitcnt lgkmcnt(2)
	v_mfma_f32_32x32x16_bf16 v[80:95], v[224:227], v[244:247], v[80:95]
	v_mfma_f32_32x32x16_bf16 v[64:79], v[224:227], v[248:251], v[64:79]
	s_waitcnt lgkmcnt(0)
	s_barrier
	v_mfma_f32_32x32x16_bf16 v[48:63], v[228:231], v[244:247], v[48:63]
	v_mfma_f32_32x32x16_bf16 v[32:47], v[228:231], v[248:251], v[32:47]
	v_mfma_f32_32x32x16_bf16 v[16:31], v[232:235], v[244:247], v[16:31]
	v_mfma_f32_32x32x16_bf16 v[0:15], v[232:235], v[248:251], v[0:15]
	s_setprio 0
	s_branch .LBB0_201

; template <int EPI, int MI>
; DI void gemm_tile(const GemmDesc& g, int tm, int tn, char* smem) {
;     ...
;   const int tid = get_tid(), lane = tid & 63, wave = tid >> 6, r = lane & 31, hh = lane >> 5;
;   const int wm = wave >> 1, wn = wave & 1;
;   const int m0 = tm * BM, n0 = tn * 128;
;   const int nk = g.K >> 6;
;   f32x16 acc[MI][2];
; #pragma unroll
;   for (int a = 0; a < MI; ++a)
; #pragma unroll
;     for (int b = 0; b < 2; ++b)
; #pragma unroll
;       for (int i = 0; i < 16; ++i) acc[a][b][i] = 0.f;
;   const int srow = tid >> 3;
;   const int schunk = (tid & 7) ^ ((srow & 7) ^ ((srow >> 3) & 3));
;     ...
;   const int rowA = wm * (32 * MI) + r, rowB = wn * 64 + r;
;   const int hk = hh ^ ((r & 7) ^ ((r >> 3) & 3));
;     ...
;   G_GLDS(0, 0);
;   asm volatile("s_waitcnt vmcnt(0)" ::: "memory");
;   __syncthreads();
; template <int EPI, int MI>
; DI void gemm_phase(const GemmDesc& g, char* smem, int vb, int nvb) {
;     ...
;   for (int q = start; q < local; q += step) {
;     const int mg = q / per;
;     const int rem = q - mg * per;
;     const int tn = rem / PM;
;     const int tm = mbase + mg * PM + (rem - tn * PM);
.LBB0_254:
	s_abs_i32 s0, s42
	v_readlane_b32 s1, v219, 48
	s_mul_hi_u32 s1, s0, s1
	v_readlane_b32 s17, v219, 47
	s_mul_i32 s4, s1, s17
	s_sub_i32 s0, s0, s4
	s_ashr_i32 s15, s42, 31
	s_add_i32 s4, s1, 1
	s_sub_i32 s5, s0, s17
	s_cmp_ge_u32 s0, s17
	s_cselect_b32 s1, s4, s1
	s_cselect_b32 s0, s5, s0
	s_add_i32 s4, s1, 1
	s_cmp_ge_u32 s0, s17
	s_cselect_b32 s0, s4, s1
	s_xor_b32 s16, s0, s15
	s_sub_i32 s0, s16, s15
	s_mul_i32 s1, s0, s17
	s_sub_i32 s1, s42, s1
	s_abs_i32 s4, s1
	v_readlane_b32 s5, v219, 46
	s_mul_hi_u32 s5, s4, s5
	v_readlane_b32 s43, v218, 32
	s_mul_i32 s18, s5, s43
	s_sub_i32 s4, s4, s18
	s_ashr_i32 s17, s1, 31
	s_add_i32 s18, s5, 1
	s_sub_i32 s19, s4, s43
	s_cmp_ge_u32 s4, s43
	s_cselect_b32 s5, s18, s5
	s_cselect_b32 s4, s19, s4
	s_add_i32 s18, s5, 1
	s_cmp_ge_u32 s4, s43
	s_cselect_b32 s4, s18, s5
	s_xor_b32 s18, s4, s17
	v_mov_b32_e32 v97, v132
	s_sub_i32 s4, s18, s17
	s_mul_i32 s0, s0, s43
	v_ashrrev_i32_e32 v6, 3, v97
	s_mul_i32 s5, s4, s43
	s_waitcnt vmcnt(8)
	v_ashrrev_i32_e32 v109, 7, v97
	v_bfe_u32 v1, v97, 6, 2
	v_xor_b32_e32 v2, v6, v97
	s_add_i32 s0, s0, s54
	s_sub_i32 s1, s1, s5
	v_and_b32_e32 v108, 31, v97
	v_bitop3_b32 v2, v2, v1, 7 bitop3:0x6c
	v_mul_lo_u32 v1, v109, s6
	s_add_i32 s1, s0, s1
	s_lshl_b32 s0, s4, 7
	v_and_b32_e32 v0, 7, v97
	v_or_b32_e32 v7, v1, v108
	v_lshrrev_b32_e32 v1, 3, v97
	v_readlane_b32 s4, v221, 5
	s_mul_i32 s43, s1, 0xc0
	v_bfe_u32 v115, v97, 5, 1
	v_bitop3_b32 v0, v1, v0, 3 bitop3:0x6c
	v_readlane_b32 s5, v221, 6
	v_xor_b32_e32 v8, v0, v115
	v_add_u32_e32 v3, s43, v6
	v_mov_b64_e32 v[0:1], s[4:5]
	s_movk_i32 s19, 0x1600
	v_mad_i64_i32 v[0:1], s[4:5], v3, s19, v[0:1]
	v_readlane_b32 s4, v221, 10
	v_readlane_b32 s5, v221, 11
	v_lshlrev_b32_e32 v98, 4, v2
	v_add_u32_e32 v9, s0, v6
	v_mov_b64_e32 v[2:3], s[4:5]
	v_lshlrev_b32_e32 v120, 4, v97
	v_mad_i64_i32 v[2:3], s[4:5], v9, s19, v[2:3]
	v_add_u32_e32 v121, 0, v120
	v_mov_b32_e32 v99, v96
	v_readfirstlane_b32 s4, v121
	v_add_u32_e32 v122, 0x1000, v121
	v_lshl_add_u64 v[0:1], v[0:1], 0, v[98:99]
	s_mov_b32 m0, s4
	s_mov_b64 s[44:45], 0x2c000
	v_readfirstlane_b32 s4, v122
	v_add_u32_e32 v123, 0x2000, v121
	global_load_lds_dwordx4 v[0:1], off
	v_lshl_add_u64 v[4:5], v[0:1], 0, s[44:45]
	s_mov_b32 m0, s4
	s_mov_b64 s[46:47], 0x58000
	v_readfirstlane_b32 s4, v123
	v_add_u32_e32 v124, 0x3000, v121
	global_load_lds_dwordx4 v[4:5], off
	v_lshl_add_u64 v[4:5], v[0:1], 0, s[46:47]
	s_mov_b32 m0, s4
	s_mov_b64 s[52:53], 0x84000
	v_readfirstlane_b32 s4, v124
	global_load_lds_dwordx4 v[4:5], off
	v_lshl_add_u64 v[4:5], v[0:1], 0, s[52:53]
	s_mov_b32 m0, s4
	s_mov_b64 s[4:5], 0xb0000
	v_add_u32_e32 v125, 0x4000, v121
	global_load_lds_dwordx4 v[4:5], off
	v_lshl_add_u64 v[4:5], v[0:1], 0, s[4:5]
	v_readfirstlane_b32 s4, v125
	s_mov_b32 m0, s4
	s_mov_b64 s[4:5], 0xdc000
	v_add_u32_e32 v126, 0x5000, v121
	v_lshl_add_u64 v[0:1], v[0:1], 0, s[4:5]
	v_readfirstlane_b32 s4, v126
	v_add_u32_e32 v127, 0xc000, v121
	global_load_lds_dwordx4 v[4:5], off
	s_mov_b32 m0, s4
	v_readfirstlane_b32 s4, v127
	v_add_u32_e32 v128, 0xd000, v121
	global_load_lds_dwordx4 v[0:1], off
	v_lshl_add_u64 v[0:1], v[2:3], 0, v[98:99]
	s_mov_b32 m0, s4
	v_readfirstlane_b32 s4, v128
	v_add_u32_e32 v129, 0xe000, v121
	global_load_lds_dwordx4 v[0:1], off
	v_lshl_add_u64 v[2:3], v[0:1], 0, s[44:45]
	s_mov_b32 m0, s4
	v_readfirstlane_b32 s4, v129
	v_add_u32_e32 v130, 0xf000, v121
	global_load_lds_dwordx4 v[2:3], off
	v_lshl_add_u64 v[2:3], v[0:1], 0, s[46:47]
	s_mov_b32 m0, s4
	v_readfirstlane_b32 s4, v130
	global_load_lds_dwordx4 v[2:3], off
	v_lshl_add_u64 v[0:1], v[0:1], 0, s[52:53]
	s_mov_b32 m0, s4
	s_mul_i32 s15, s15, 7
	global_load_lds_dwordx4 v[0:1], off
	s_add_i32 s17, s17, s15
	s_sub_i32 s4, s17, s18
	s_mul_i32 s16, s16, 7
	s_sub_i32 s4, s4, s16
	v_readlane_b32 s5, v218, 33
	v_lshlrev_b32_e32 v0, 7, v97
	s_mul_i32 s4, s5, s4
	v_and_b32_e32 v0, 0x2f80, v0
	s_add_i32 s4, s4, s39
	s_waitcnt vmcnt(0)
	v_add_u32_e32 v153, 0, v0
	v_add_u32_e32 v155, s10, v0
	v_add_u32_e32 v2, s4, v6
	v_mov_b64_e32 v[0:1], s[70:71]
	v_lshlrev_b32_e32 v154, 4, v8
	v_mad_i64_i32 v[100:101], s[4:5], v2, s19, v[0:1]
	v_mad_i64_i32 v[102:103], s[4:5], v9, s19, v[0:1]
	v_mov_b32_e32 v0, 0
	v_lshl_add_u32 v131, v7, 7, 0
	v_xor_b32_e32 v156, 32, v154
	v_xor_b32_e32 v157, 64, v154
	v_xor_b32_e32 v158, 0x60, v154
	s_mov_b32 s15, 0
	v_mov_b32_e32 v1, v0
	v_mov_b32_e32 v2, v0
	v_mov_b32_e32 v3, v0
	v_mov_b32_e32 v4, v0
	v_mov_b32_e32 v5, v0
	v_mov_b32_e32 v6, v0
	v_mov_b32_e32 v7, v0
	v_mov_b32_e32 v8, v0
	v_mov_b32_e32 v9, v0
	v_mov_b32_e32 v10, v0
	v_mov_b32_e32 v11, v0
	v_mov_b32_e32 v12, v0
	v_mov_b32_e32 v13, v0
	v_mov_b32_e32 v14, v0
	v_mov_b32_e32 v15, v0
	v_mov_b32_e32 v16, v0
	v_mov_b32_e32 v17, v0
	v_mov_b32_e32 v18, v0
	v_mov_b32_e32 v19, v0
	v_mov_b32_e32 v20, v0
	v_mov_b32_e32 v21, v0
	v_mov_b32_e32 v22, v0
	v_mov_b32_e32 v23, v0
	v_mov_b32_e32 v24, v0
	v_mov_b32_e32 v25, v0
	v_mov_b32_e32 v26, v0
	v_mov_b32_e32 v27, v0
	v_mov_b32_e32 v28, v0
	v_mov_b32_e32 v29, v0
	v_mov_b32_e32 v30, v0
	v_mov_b32_e32 v31, v0
	v_mov_b32_e32 v32, v0
	v_mov_b32_e32 v33, v0
	v_mov_b32_e32 v34, v0
	v_mov_b32_e32 v35, v0
	v_mov_b32_e32 v36, v0
	v_mov_b32_e32 v37, v0
	v_mov_b32_e32 v38, v0
	v_mov_b32_e32 v39, v0
	v_mov_b32_e32 v40, v0
	v_mov_b32_e32 v41, v0
	v_mov_b32_e32 v42, v0
	v_mov_b32_e32 v43, v0
	v_mov_b32_e32 v44, v0
	v_mov_b32_e32 v45, v0
	v_mov_b32_e32 v46, v0
	v_mov_b32_e32 v47, v0
	v_mov_b32_e32 v48, v0
	s_waitcnt vmcnt(0)
	v_mov_b32_e32 v49, v0
	v_mov_b32_e32 v50, v0
	v_mov_b32_e32 v51, v0
	v_mov_b32_e32 v52, v0
	v_mov_b32_e32 v53, v0
	v_mov_b32_e32 v54, v0
	v_mov_b32_e32 v55, v0
	v_mov_b32_e32 v56, v0
	v_mov_b32_e32 v57, v0
	v_mov_b32_e32 v58, v0
	v_mov_b32_e32 v59, v0
	v_mov_b32_e32 v60, v0
	v_mov_b32_e32 v61, v0
	v_mov_b32_e32 v62, v0
	v_mov_b32_e32 v63, v0
	v_mov_b32_e32 v64, v0
	v_mov_b32_e32 v65, v0
	v_mov_b32_e32 v66, v0
	v_mov_b32_e32 v67, v0
	v_mov_b32_e32 v68, v0
	v_mov_b32_e32 v69, v0
	v_mov_b32_e32 v70, v0
	v_mov_b32_e32 v71, v0
	v_mov_b32_e32 v72, v0
	v_mov_b32_e32 v73, v0
	v_mov_b32_e32 v74, v0
	v_mov_b32_e32 v75, v0
	v_mov_b32_e32 v76, v0
	v_mov_b32_e32 v77, v0
	v_mov_b32_e32 v78, v0
	v_mov_b32_e32 v79, v0
	v_mov_b32_e32 v80, v0
	v_mov_b32_e32 v81, v0
	v_mov_b32_e32 v82, v0
	v_mov_b32_e32 v83, v0
	v_mov_b32_e32 v84, v0
	v_mov_b32_e32 v85, v0
	v_mov_b32_e32 v86, v0
	v_mov_b32_e32 v87, v0
	v_mov_b32_e32 v88, v0
	v_mov_b32_e32 v89, v0
	v_mov_b32_e32 v90, v0
	v_mov_b32_e32 v91, v0
	v_mov_b32_e32 v92, v0
	v_mov_b32_e32 v93, v0
	v_mov_b32_e32 v94, v0
	v_mov_b32_e32 v95, v0
	v_readlane_b32 s100, v218, 17
	s_nop 3
	s_cmp_lt_i32 s100, 0
	s_cbranch_scc0 .Lgd_noprio
	s_setprio 1
; template <int EPI, int MI>
; DI void gemm_tile(const GemmDesc& g, int tm, int tn, char* smem) {
;     ...
;   const int rowA = wm * (32 * MI) + r, rowB = wn * 64 + r;
;   const int hk = hh ^ ((r & 7) ^ ((r >> 3) & 3));
;     ...
;   G_GLDS(0, 0);
;   asm volatile("s_waitcnt vmcnt(0)" ::: "memory");
;   __syncthreads();
.Lgd_noprio:
	v_add_u32_e32 v162, v131, v154
	v_add_u32_e32 v163, v131, v156
	v_add_u32_e32 v164, v131, v157
	v_add_u32_e32 v165, v131, v158
	v_add_u32_e32 v166, v153, v154
	v_add_u32_e32 v167, v153, v156
	v_add_u32_e32 v168, v153, v157
	v_add_u32_e32 v169, v153, v158
	v_add_u32_e32 v170, v155, v154
	v_add_u32_e32 v171, v155, v156
	v_add_u32_e32 v172, v155, v157
	v_add_u32_e32 v173, v155, v158
	v_lshl_add_u64 v[252:253], v[100:101], 0, v[98:99]
	v_lshl_add_u64 v[254:255], v[102:103], 0, v[98:99]
	v_readfirstlane_b32 s100, v121
	s_mov_b64 s[4:5], 0x80
	s_waitcnt vmcnt(0) lgkmcnt(0)
	s_barrier
	s_mov_b64 s[16:17], 0x5872080
	s_add_u32 m0, s100, 0x6000
	v_lshl_add_u64 v[106:107], v[252:253], 0, s[16:17]
	global_load_lds_dwordx4 v[106:107], off
	s_mov_b64 s[16:17], 0x589e080
	s_add_u32 m0, s100, 0x7000
	v_lshl_add_u64 v[106:107], v[252:253], 0, s[16:17]
	global_load_lds_dwordx4 v[106:107], off
	ds_read_b128 v[236:239], v166 offset:49152
	ds_read_b128 v[240:243], v166 offset:53248
	ds_read_b128 v[224:227], v162
	ds_read_b128 v[228:231], v162 offset:4096
	s_mov_b32 s15, 0

; template <int EPI, int MI>
; DI void gemm_tile(const GemmDesc& g, int tm, int tn, char* smem) {
;     ...
;   const int tid = get_tid(), lane = tid & 63, wave = tid >> 6, r = lane & 31, hh = lane >> 5;
;   const int wm = wave >> 1, wn = wave & 1;
;   const int m0 = tm * BM, n0 = tn * 128;
;   const int nk = g.K >> 6;
;   f32x16 acc[MI][2];
; #pragma unroll
;   for (int a = 0; a < MI; ++a)
; #pragma unroll
;     for (int b = 0; b < 2; ++b)
; #pragma unroll
;       for (int i = 0; i < 16; ++i) acc[a][b][i] = 0.f;
;   const int srow = tid >> 3;
;   const int schunk = (tid & 7) ^ ((srow & 7) ^ ((srow >> 3) & 3));
;     ...
;   const int rowA = wm * (32 * MI) + r, rowB = wn * 64 + r;
;   const int hk = hh ^ ((r & 7) ^ ((r >> 3) & 3));
;     ...
;   G_GLDS(0, 0);
;   asm volatile("s_waitcnt vmcnt(0)" ::: "memory");
;   __syncthreads();
; template <int EPI, int MI>
; DI void gemm_phase(const GemmDesc& g, char* smem, int vb, int nvb) {
;     ...
;   for (int q = start; q < local; q += step) {
;     const int mg = q / per;
;     const int rem = q - mg * per;
;     const int tn = rem / PM;
;     const int tm = mbase + mg * PM + (rem - tn * PM);
.LBB0_371:
	s_abs_i32 s1, s47
	s_mul_hi_u32 s4, s1, s45
	s_mul_i32 s5, s4, s43
	s_sub_i32 s1, s1, s5
	s_ashr_i32 s0, s47, 31
	s_add_i32 s5, s4, 1
	s_sub_i32 s15, s1, s43
	s_cmp_ge_u32 s1, s43
	s_cselect_b32 s4, s5, s4
	s_cselect_b32 s1, s15, s1
	s_add_i32 s5, s4, 1
	s_cmp_ge_u32 s1, s43
	s_cselect_b32 s1, s5, s4
	s_xor_b32 s1, s1, s0
	s_sub_i32 s4, s1, s0
	s_mul_i32 s5, s4, s43
	s_sub_i32 s5, s47, s5
	s_abs_i32 s16, s5
	v_readlane_b32 s17, v219, 46
	s_mul_hi_u32 s17, s16, s17
	v_readlane_b32 s38, v218, 32
	s_mul_i32 s18, s17, s38
	s_sub_i32 s16, s16, s18
	s_ashr_i32 s15, s5, 31
	s_add_i32 s18, s17, 1
	s_sub_i32 s19, s16, s38
	s_cmp_ge_u32 s16, s38
	s_cselect_b32 s17, s18, s17
	s_cselect_b32 s16, s19, s16
	s_add_i32 s18, s17, 1
	s_cmp_ge_u32 s16, s38
	s_cselect_b32 s16, s18, s17
	s_xor_b32 s16, s16, s15
	s_sub_i32 s17, s16, s15
	s_sub_i32 s18, s4, s17
	v_mov_b32_e32 v97, v132
	s_mul_i32 s18, s18, s38
	s_add_i32 s5, s5, s54
	s_add_i32 s48, s5, s18
	v_ashrrev_i32_e32 v0, 7, v97
	v_and_b32_e32 v1, 7, v97
	v_mul_lo_u32 v115, v0, s6
	v_lshrrev_b32_e32 v0, 3, v97
	s_mulk_i32 s48, 0xc0
	s_waitcnt vmcnt(8)
	v_bfe_u32 v109, v97, 5, 1
	v_ashrrev_i32_e32 v8, 3, v97
	v_bitop3_b32 v0, v0, v1, 3 bitop3:0x6c
	v_bfe_u32 v2, v97, 6, 2
	v_xor_b32_e32 v3, v8, v97
	v_xor_b32_e32 v10, v0, v109
	v_add_u32_e32 v0, s48, v8
	s_lshl_b32 s49, s17, 7
	v_bitop3_b32 v2, v3, v2, 7 bitop3:0x6c
	v_ashrrev_i32_e32 v1, 31, v0
	v_readlane_b32 s18, v223, 59
	v_lshlrev_b64 v[0:1], 11, v[0:1]
	v_readlane_b32 s19, v223, 60
	v_lshlrev_b32_e32 v98, 4, v2
	v_add_u32_e32 v2, s49, v8
	v_lshlrev_b32_e32 v120, 4, v97
	v_lshl_add_u64 v[0:1], s[18:19], 0, v[0:1]
	v_ashrrev_i32_e32 v3, 31, v2
	v_readlane_b32 s18, v221, 16
	v_add_u32_e32 v121, 0, v120
	v_mov_b32_e32 v99, v96
	v_lshlrev_b64 v[2:3], 11, v[2:3]
	v_readlane_b32 s19, v221, 17
	v_readfirstlane_b32 s5, v121
	v_add_u32_e32 v122, 0x1000, v121
	v_lshl_add_u64 v[0:1], v[0:1], 0, v[98:99]
	v_lshl_add_u64 v[4:5], s[18:19], 0, v[2:3]
	s_mov_b32 m0, s5
	s_mov_b64 s[18:19], 0x10000
	v_readfirstlane_b32 s5, v122
	v_add_u32_e32 v123, 0x2000, v121
	global_load_lds_dwordx4 v[0:1], off
	v_lshl_add_u64 v[6:7], v[0:1], 0, s[18:19]
	s_mov_b32 m0, s5
	s_mov_b64 s[38:39], 0x20000
	v_readfirstlane_b32 s5, v123
	v_add_u32_e32 v124, 0x3000, v121
	global_load_lds_dwordx4 v[6:7], off
	v_lshl_add_u64 v[6:7], v[0:1], 0, s[38:39]
	s_mov_b32 m0, s5
	s_mov_b64 s[52:53], 0x30000
	v_readfirstlane_b32 s5, v124
	v_add_u32_e32 v125, 0x4000, v121
	global_load_lds_dwordx4 v[6:7], off
	v_lshl_add_u64 v[6:7], v[0:1], 0, s[52:53]
	s_mov_b32 m0, s5
	s_mov_b64 s[72:73], 0x40000
	v_readfirstlane_b32 s5, v125
	v_add_u32_e32 v126, 0x5000, v121
	global_load_lds_dwordx4 v[6:7], off
	v_lshl_add_u64 v[6:7], v[0:1], 0, s[72:73]
	s_mov_b32 m0, s5
	s_mov_b64 s[72:73], 0x50000
	v_readfirstlane_b32 s5, v126
	v_add_u32_e32 v127, 0xc000, v121
	global_load_lds_dwordx4 v[6:7], off
	v_lshl_add_u64 v[0:1], v[0:1], 0, s[72:73]
	s_mov_b32 m0, s5
	v_readfirstlane_b32 s5, v127
	v_add_u32_e32 v128, 0xd000, v121
	global_load_lds_dwordx4 v[0:1], off
	v_lshl_add_u64 v[0:1], v[4:5], 0, v[98:99]
	s_mov_b32 m0, s5
	v_readfirstlane_b32 s5, v128
	v_add_u32_e32 v129, 0xe000, v121
	global_load_lds_dwordx4 v[0:1], off
	v_lshl_add_u64 v[4:5], v[0:1], 0, s[18:19]
	s_mov_b32 m0, s5
	v_readfirstlane_b32 s5, v129
	v_add_u32_e32 v130, 0xf000, v121
	global_load_lds_dwordx4 v[4:5], off
	v_lshl_add_u64 v[4:5], v[0:1], 0, s[38:39]
	s_mov_b32 m0, s5
	v_readfirstlane_b32 s5, v130
	global_load_lds_dwordx4 v[4:5], off
	v_lshl_add_u64 v[0:1], v[0:1], 0, s[52:53]
	s_mov_b32 m0, s5
	s_add_i32 s1, s1, s15
	global_load_lds_dwordx4 v[0:1], off
	s_mul_i32 s4, s20, s4
	s_sub_i32 s1, s1, s4
	s_sub_i32 s1, s1, s16
	s_sub_i32 s0, s1, s0
	v_readlane_b32 s1, v218, 33
	v_lshlrev_b32_e32 v0, 7, v97
	s_mul_i32 s0, s1, s0
	v_and_b32_e32 v0, 0x2f80, v0
	s_add_i32 s0, s0, s46
	v_add_u32_e32 v153, 0, v0
	v_add_u32_e32 v155, s10, v0
	v_add_u32_e32 v0, s0, v8
	v_ashrrev_i32_e32 v1, 31, v0
	v_and_b32_e32 v108, 31, v97
	s_waitcnt vmcnt(0)
	v_lshlrev_b64 v[0:1], 11, v[0:1]
	v_or_b32_e32 v9, v115, v108
	v_lshlrev_b32_e32 v154, 4, v10
	v_lshl_add_u64 v[102:103], s[70:71], 0, v[0:1]
	v_mov_b32_e32 v0, 0
	v_lshl_add_u32 v131, v9, 7, 0
	v_xor_b32_e32 v156, 32, v154
	v_xor_b32_e32 v157, 64, v154
	v_xor_b32_e32 v158, 0x60, v154
	v_lshl_add_u64 v[100:101], s[70:71], 0, v[2:3]
	s_mov_b32 s4, 0
	v_mov_b32_e32 v1, v0
	v_mov_b32_e32 v2, v0
	v_mov_b32_e32 v3, v0
	v_mov_b32_e32 v4, v0
	v_mov_b32_e32 v5, v0
	v_mov_b32_e32 v6, v0
	v_mov_b32_e32 v7, v0
	v_mov_b32_e32 v8, v0
	v_mov_b32_e32 v9, v0
	v_mov_b32_e32 v10, v0
	v_mov_b32_e32 v11, v0
	v_mov_b32_e32 v12, v0
	v_mov_b32_e32 v13, v0
	v_mov_b32_e32 v14, v0
	v_mov_b32_e32 v15, v0
	v_mov_b32_e32 v16, v0
	v_mov_b32_e32 v17, v0
	v_mov_b32_e32 v18, v0
	v_mov_b32_e32 v19, v0
	v_mov_b32_e32 v20, v0
	v_mov_b32_e32 v21, v0
	v_mov_b32_e32 v22, v0
	v_mov_b32_e32 v23, v0
	v_mov_b32_e32 v24, v0
	v_mov_b32_e32 v25, v0
	v_mov_b32_e32 v26, v0
	v_mov_b32_e32 v27, v0
	v_mov_b32_e32 v28, v0
	v_mov_b32_e32 v29, v0
	v_mov_b32_e32 v30, v0
	v_mov_b32_e32 v31, v0
	v_mov_b32_e32 v32, v0
	v_mov_b32_e32 v33, v0
	v_mov_b32_e32 v34, v0
	v_mov_b32_e32 v35, v0
	v_mov_b32_e32 v36, v0
	v_mov_b32_e32 v37, v0
	v_mov_b32_e32 v38, v0
	v_mov_b32_e32 v39, v0
	v_mov_b32_e32 v40, v0
	v_mov_b32_e32 v41, v0
	v_mov_b32_e32 v42, v0
	v_mov_b32_e32 v43, v0
	v_mov_b32_e32 v44, v0
	v_mov_b32_e32 v45, v0
	v_mov_b32_e32 v46, v0
	v_mov_b32_e32 v47, v0
	v_mov_b32_e32 v48, v0
	s_waitcnt vmcnt(0)
	v_mov_b32_e32 v49, v0
	v_mov_b32_e32 v50, v0
	v_mov_b32_e32 v51, v0
	v_mov_b32_e32 v52, v0
	v_mov_b32_e32 v53, v0
	v_mov_b32_e32 v54, v0
	v_mov_b32_e32 v55, v0
	v_mov_b32_e32 v56, v0
	v_mov_b32_e32 v57, v0
	v_mov_b32_e32 v58, v0
	v_mov_b32_e32 v59, v0
	v_mov_b32_e32 v60, v0
	v_mov_b32_e32 v61, v0
	v_mov_b32_e32 v62, v0
	v_mov_b32_e32 v63, v0
	v_mov_b32_e32 v64, v0
	v_mov_b32_e32 v65, v0
	v_mov_b32_e32 v66, v0
	v_mov_b32_e32 v67, v0
	v_mov_b32_e32 v68, v0
	v_mov_b32_e32 v69, v0
	v_mov_b32_e32 v70, v0
	v_mov_b32_e32 v71, v0
	v_mov_b32_e32 v72, v0
	v_mov_b32_e32 v73, v0
	v_mov_b32_e32 v74, v0
	v_mov_b32_e32 v75, v0
	v_mov_b32_e32 v76, v0
	v_mov_b32_e32 v77, v0
	v_mov_b32_e32 v78, v0
	v_mov_b32_e32 v79, v0
	v_mov_b32_e32 v80, v0
	v_mov_b32_e32 v81, v0
	v_mov_b32_e32 v82, v0
	v_mov_b32_e32 v83, v0
	v_mov_b32_e32 v84, v0
	v_mov_b32_e32 v85, v0
	v_mov_b32_e32 v86, v0
	v_mov_b32_e32 v87, v0
	v_mov_b32_e32 v88, v0
	v_mov_b32_e32 v89, v0
	v_mov_b32_e32 v90, v0
	v_mov_b32_e32 v91, v0
	v_mov_b32_e32 v92, v0
	v_mov_b32_e32 v93, v0
	v_mov_b32_e32 v94, v0
	v_mov_b32_e32 v95, v0
	v_readlane_b32 s100, v218, 17
	s_nop 3
	s_cmp_lt_i32 s100, 0
	s_cbranch_scc0 .Lgw_noprio
	s_setprio 1
; template <int EPI, int MI>
; DI void gemm_tile(const GemmDesc& g, int tm, int tn, char* smem) {
;     ...
;   const int rowA = wm * (32 * MI) + r, rowB = wn * 64 + r;
;   const int hk = hh ^ ((r & 7) ^ ((r >> 3) & 3));
;     ...
;   G_GLDS(0, 0);
;   asm volatile("s_waitcnt vmcnt(0)" ::: "memory");
;   __syncthreads();
.Lgw_noprio:
	v_add_u32_e32 v162, v131, v154
	v_add_u32_e32 v163, v131, v156
	v_add_u32_e32 v164, v131, v157
	v_add_u32_e32 v165, v131, v158
	v_add_u32_e32 v166, v153, v154
	v_add_u32_e32 v167, v153, v156
	v_add_u32_e32 v168, v153, v157
	v_add_u32_e32 v169, v153, v158
	v_add_u32_e32 v170, v155, v154
	v_add_u32_e32 v171, v155, v156
	v_add_u32_e32 v172, v155, v157
	v_add_u32_e32 v173, v155, v158
	v_lshl_add_u64 v[252:253], v[102:103], 0, v[98:99]
	v_lshl_add_u64 v[254:255], v[100:101], 0, v[98:99]
	v_readfirstlane_b32 s100, v121
	s_mov_b64 s[0:1], 0x80
	s_waitcnt vmcnt(0) lgkmcnt(0)
	s_barrier
	s_add_u32 m0, s100, 0x6000
	v_lshl_add_u64 v[106:107], v[252:253], 0, s[96:97]
	global_load_lds_dwordx4 v[106:107], off
	s_add_u32 m0, s100, 0x7000
	v_lshl_add_u64 v[106:107], v[252:253], 0, s[50:51]
	global_load_lds_dwordx4 v[106:107], off
	ds_read_b128 v[236:239], v166 offset:49152
	ds_read_b128 v[240:243], v166 offset:53248
	ds_read_b128 v[224:227], v162
	ds_read_b128 v[228:231], v162 offset:4096
	s_mov_b32 s101, 0

; template <int EPI, int MI>
; DI void gemm_tile(const GemmDesc& g, int tm, int tn, char* smem) {
;     ...
;   const int tid = get_tid(), lane = tid & 63, wave = tid >> 6, r = lane & 31, hh = lane >> 5;
;   const int wm = wave >> 1, wn = wave & 1;
;   const int m0 = tm * BM, n0 = tn * 128;
;   const int nk = g.K >> 6;
;   f32x16 acc[MI][2];
; #pragma unroll
;   for (int a = 0; a < MI; ++a)
; #pragma unroll
;     for (int b = 0; b < 2; ++b)
; #pragma unroll
;       for (int i = 0; i < 16; ++i) acc[a][b][i] = 0.f;
;   const int srow = tid >> 3;
;   const int schunk = (tid & 7) ^ ((srow & 7) ^ ((srow >> 3) & 3));
;     ...
;   const int rowA = wm * (32 * MI) + r, rowB = wn * 64 + r;
;   const int hk = hh ^ ((r & 7) ^ ((r >> 3) & 3));
;     ...
;   G_GLDS(0, 0);
;   asm volatile("s_waitcnt vmcnt(0)" ::: "memory");
;   __syncthreads();
; template <int EPI, int MI>
; DI void gemm_phase(const GemmDesc& g, char* smem, int vb, int nvb) {
;     ...
;   for (int q = start; q < local; q += step) {
;     const int mg = q / per;
;     const int rem = q - mg * per;
;     const int tn = rem / PM;
;     const int tm = mbase + mg * PM + (rem - tn * PM);
.LBB0_1410:
	s_abs_i32 s1, s39
	s_mul_hi_u32 s40, s1, s17
	s_mul_i32 s41, s40, s15
	s_sub_i32 s1, s1, s41
	s_ashr_i32 s0, s39, 31
	s_add_i32 s41, s40, 1
	s_sub_i32 s42, s1, s15
	s_cmp_ge_u32 s1, s15
	s_cselect_b32 s40, s41, s40
	s_cselect_b32 s1, s42, s1
	s_add_i32 s41, s40, 1
	s_cmp_ge_u32 s1, s15
	s_cselect_b32 s1, s41, s40
	s_xor_b32 s1, s1, s0
	s_sub_i32 s40, s1, s0
	s_mul_i32 s41, s40, s15
	s_sub_i32 s42, s39, s41
	s_abs_i32 s41, s42
	s_mul_hi_u32 s44, s41, s18
	s_mul_i32 s45, s44, s4
	s_sub_i32 s41, s41, s45
	s_ashr_i32 s43, s42, 31
	s_add_i32 s45, s44, 1
	s_sub_i32 s46, s41, s4
	s_cmp_ge_u32 s41, s4
	s_cselect_b32 s44, s45, s44
	s_cselect_b32 s41, s46, s41
	s_add_i32 s45, s44, 1
	s_cmp_ge_u32 s41, s4
	s_cselect_b32 s41, s45, s44
	s_xor_b32 s44, s41, s43
	s_sub_i32 s41, s44, s43
	s_sub_i32 s40, s40, s41
	v_mov_b32_e32 v6, v132
	s_mul_i32 s40, s40, s4
	s_add_i32 s42, s42, s16
	s_add_i32 s42, s42, s40
	v_ashrrev_i32_e32 v76, 3, v6
	v_bfe_u32 v0, v6, 6, 2
	v_xor_b32_e32 v1, v76, v6
	s_lshl_b32 s40, s42, 7
	v_bitop3_b32 v2, v1, v0, 7 bitop3:0x6c
	v_ashrrev_i32_e32 v0, 1, v6
	v_and_b32_e32 v77, 7, v6
	v_and_b32_e32 v79, 0xffffffc0, v0
	v_lshrrev_b32_e32 v0, 3, v6
	v_add_u32_e32 v64, s40, v76
	v_bfe_u32 v78, v6, 5, 1
	v_bitop3_b32 v0, v0, v77, 3 bitop3:0x6c
	v_ashrrev_i32_e32 v65, 31, v64
	v_readlane_b32 s46, v223, 59
	v_and_b32_e32 v80, 31, v6
	v_bfe_u32 v81, v6, 6, 1
	v_xor_b32_e32 v9, v0, v78
	v_lshlrev_b64 v[0:1], 11, v[64:65]
	v_readlane_b32 s47, v223, 60
	v_lshlrev_b32_e32 v66, 4, v2
	v_lshl_add_u32 v2, s41, 7, v76
	v_lshlrev_b32_e32 v6, 4, v6
	v_lshl_add_u64 v[0:1], s[46:47], 0, v[0:1]
	v_ashrrev_i32_e32 v3, 31, v2
	v_readlane_b32 s46, v220, 54
	v_add_u32_e32 v65, 0, v6
	v_mov_b32_e32 v67, v96
	v_lshlrev_b64 v[2:3], 11, v[2:3]
	v_readlane_b32 s47, v220, 55
	v_readfirstlane_b32 s42, v65
	v_add_u32_e32 v82, 0x1000, v65
	v_lshl_add_u64 v[0:1], v[0:1], 0, v[66:67]
	v_lshl_add_u64 v[4:5], s[46:47], 0, v[2:3]
	s_mov_b32 m0, s42
	s_mov_b64 s[46:47], 0x10000
	v_readfirstlane_b32 s42, v82
	v_add_u32_e32 v83, 0x2000, v65
	global_load_lds_dwordx4 v[0:1], off
	v_lshl_add_u64 v[6:7], v[0:1], 0, s[46:47]
	s_mov_b32 m0, s42
	s_mov_b64 s[52:53], 0x20000
	v_readfirstlane_b32 s42, v83
	v_add_u32_e32 v84, 0x3000, v65
	global_load_lds_dwordx4 v[6:7], off
	v_lshl_add_u64 v[6:7], v[0:1], 0, s[52:53]
	s_mov_b32 m0, s42
	s_mov_b64 s[72:73], 0x30000
	v_readfirstlane_b32 s42, v84
	v_add_u32_e32 v85, 0x8000, v65
	global_load_lds_dwordx4 v[6:7], off
	v_lshl_add_u64 v[0:1], v[0:1], 0, s[72:73]
	s_mov_b32 m0, s42
	v_readfirstlane_b32 s42, v85
	v_add_u32_e32 v86, 0x9000, v65
	global_load_lds_dwordx4 v[0:1], off
	v_lshl_add_u64 v[0:1], v[4:5], 0, v[66:67]
	s_mov_b32 m0, s42
	v_readfirstlane_b32 s42, v86
	v_add_u32_e32 v87, 0xa000, v65
	global_load_lds_dwordx4 v[0:1], off
	v_lshl_add_u64 v[4:5], v[0:1], 0, s[46:47]
	s_mov_b32 m0, s42
	v_readfirstlane_b32 s42, v87
	v_add_u32_e32 v88, 0xb000, v65
	global_load_lds_dwordx4 v[4:5], off
	v_lshl_add_u64 v[4:5], v[0:1], 0, s[52:53]
	s_mov_b32 m0, s42
	v_readfirstlane_b32 s42, v88
	global_load_lds_dwordx4 v[4:5], off
	v_lshl_add_u64 v[0:1], v[0:1], 0, s[72:73]
	s_mov_b32 m0, s42
	s_mul_i32 s0, s0, 43
	global_load_lds_dwordx4 v[0:1], off
	s_add_i32 s43, s43, s0
	s_sub_i32 s0, s43, s44
	s_mul_i32 s1, s1, 43
	s_sub_i32 s0, s0, s1
	v_lshlrev_b32_e32 v0, 7, v80
	s_mul_i32 s0, s38, s0
	v_lshl_or_b32 v0, v81, 13, v0
	s_add_i32 s0, s0, s19
	v_add_u32_e32 v90, 0, v0
	v_add_u32_e32 v0, s0, v76
	v_ashrrev_i32_e32 v1, 31, v0
	s_waitcnt vmcnt(0)
	v_lshlrev_b64 v[0:1], 11, v[0:1]
	v_or_b32_e32 v8, v79, v80
	v_lshlrev_b32_e32 v91, 4, v9
	v_lshl_add_u64 v[68:69], s[70:71], 0, v[0:1]
	v_mov_b32_e32 v0, 0
	v_lshl_add_u32 v89, v8, 7, 0
	v_xor_b32_e32 v92, 32, v91
	v_xor_b32_e32 v93, 64, v91
	v_xor_b32_e32 v94, 0x60, v91
	v_lshl_add_u64 v[70:71], s[70:71], 0, v[2:3]
	s_mov_b32 s42, 0
	v_mov_b32_e32 v1, v0
	v_mov_b32_e32 v2, v0
	v_mov_b32_e32 v3, v0
	v_mov_b32_e32 v4, v0
	v_mov_b32_e32 v5, v0
	v_mov_b32_e32 v6, v0
	v_mov_b32_e32 v7, v0
	v_mov_b32_e32 v8, v0
	v_mov_b32_e32 v9, v0
	v_mov_b32_e32 v10, v0
	v_mov_b32_e32 v11, v0
	v_mov_b32_e32 v12, v0
	v_mov_b32_e32 v13, v0
	v_mov_b32_e32 v14, v0
	v_mov_b32_e32 v15, v0
	v_mov_b32_e32 v16, v0
	v_mov_b32_e32 v17, v0
	v_mov_b32_e32 v18, v0
	v_mov_b32_e32 v19, v0
	v_mov_b32_e32 v20, v0
	v_mov_b32_e32 v21, v0
	v_mov_b32_e32 v22, v0
	v_mov_b32_e32 v23, v0
	v_mov_b32_e32 v24, v0
	v_mov_b32_e32 v25, v0
	v_mov_b32_e32 v26, v0
	v_mov_b32_e32 v27, v0
	v_mov_b32_e32 v28, v0
	v_mov_b32_e32 v29, v0
	v_mov_b32_e32 v30, v0
	v_mov_b32_e32 v31, v0
	v_mov_b32_e32 v32, v0
	v_mov_b32_e32 v33, v0
	v_mov_b32_e32 v34, v0
	v_mov_b32_e32 v35, v0
	v_mov_b32_e32 v36, v0
	v_mov_b32_e32 v37, v0
	v_mov_b32_e32 v38, v0
	v_mov_b32_e32 v39, v0
	v_mov_b32_e32 v40, v0
	v_mov_b32_e32 v41, v0
	v_mov_b32_e32 v42, v0
	v_mov_b32_e32 v43, v0
	v_mov_b32_e32 v44, v0
	v_mov_b32_e32 v45, v0
	v_mov_b32_e32 v46, v0
	v_mov_b32_e32 v47, v0
	v_mov_b32_e32 v48, v0
	v_mov_b32_e32 v49, v0
	v_mov_b32_e32 v50, v0
	v_mov_b32_e32 v51, v0
	v_mov_b32_e32 v52, v0
	v_mov_b32_e32 v53, v0
	v_mov_b32_e32 v54, v0
	v_mov_b32_e32 v55, v0
	v_mov_b32_e32 v56, v0
	v_mov_b32_e32 v57, v0
	v_mov_b32_e32 v58, v0
	v_mov_b32_e32 v59, v0
	v_mov_b32_e32 v60, v0
	v_mov_b32_e32 v61, v0
	v_mov_b32_e32 v62, v0
	v_mov_b32_e32 v63, v0
	v_readlane_b32 s100, v218, 17
	s_nop 3
	s_cmp_lt_i32 s100, 0
	s_cbranch_scc0 .Lgc_noprio
	s_setprio 1
.Lgc_noprio:
	v_add_u32_e32 v98, v89, v91
	v_add_u32_e32 v99, v89, v92
	v_add_u32_e32 v100, v89, v93
	v_add_u32_e32 v101, v89, v94
	v_add_u32_e32 v102, v90, v91
	v_add_u32_e32 v103, v90, v92
	v_add_u32_e32 v104, v90, v93
	v_add_u32_e32 v105, v90, v94
	v_lshl_add_u64 v[72:73], v[68:69], 0, v[66:67]
	v_lshl_add_u64 v[74:75], v[70:71], 0, v[66:67]
	v_readfirstlane_b32 s100, v65
	s_mov_b64 s[44:45], 0x80
	s_waitcnt vmcnt(0) lgkmcnt(0)
	s_barrier
	s_add_u32 m0, s100, 0x4000
	v_lshl_add_u64 v[106:107], v[72:73], 0, s[96:97]
	global_load_lds_dwordx4 v[106:107], off
	s_add_u32 m0, s100, 0x5000
	v_lshl_add_u64 v[106:107], v[72:73], 0, s[50:51]
	global_load_lds_dwordx4 v[106:107], off
	ds_read_b128 v[240:243], v102 offset:32768
	ds_read_b128 v[244:247], v102 offset:36864
	ds_read_b128 v[224:227], v98
	ds_read_b128 v[228:231], v98 offset:4096
	s_mov_b32 s101, 0

; template <int EPI, int MI>
; DI void gemm_tile(const GemmDesc& g, int tm, int tn, char* smem) {
;     ...
;   for (int kt = 0; kt < nk; kt += 2) {
;     if (kt + 1 < nk) G_GLDS(kt + 1, 1);
;     G_COMPUTE(0);
;     asm volatile("s_waitcnt vmcnt(0)" ::: "memory");
;     __syncthreads();
;     if (kt + 1 < nk) {
;       if (kt + 2 < nk) G_GLDS(kt + 2, 0);
;       G_COMPUTE(1);
;       asm volatile("s_waitcnt vmcnt(0)" ::: "memory");
;       __syncthreads();
;     }
;   }
.Lgc_last:
	ds_read_b128 v[248:251], v103 offset:49152
	ds_read_b128 v[252:255], v103 offset:53248
	ds_read_b128 v[232:235], v99 offset:16384
	s_waitcnt lgkmcnt(4)
	v_mfma_f32_32x32x16_bf16 v[48:63], v[224:227], v[240:243], v[48:63]
	v_mfma_f32_32x32x16_bf16 v[32:47], v[224:227], v[244:247], v[32:47]
	ds_read_b128 v[236:239], v99 offset:20480
	s_waitcnt lgkmcnt(4)
	v_mfma_f32_32x32x16_bf16 v[16:31], v[228:231], v[240:243], v[16:31]
	v_mfma_f32_32x32x16_bf16 v[0:15], v[228:231], v[244:247], v[0:15]
	ds_read_b128 v[240:243], v104 offset:49152
	ds_read_b128 v[244:247], v104 offset:53248
	ds_read_b128 v[224:227], v100 offset:16384
	s_waitcnt lgkmcnt(4)
	v_mfma_f32_32x32x16_bf16 v[48:63], v[232:235], v[248:251], v[48:63]
	v_mfma_f32_32x32x16_bf16 v[32:47], v[232:235], v[252:255], v[32:47]
	ds_read_b128 v[228:231], v100 offset:20480
	s_waitcnt lgkmcnt(4)
	v_mfma_f32_32x32x16_bf16 v[16:31], v[236:239], v[248:251], v[16:31]
	v_mfma_f32_32x32x16_bf16 v[0:15], v[236:239], v[252:255], v[0:15]
	ds_read_b128 v[248:251], v105 offset:49152
	ds_read_b128 v[252:255], v105 offset:53248
	ds_read_b128 v[232:235], v101 offset:16384
	s_waitcnt lgkmcnt(4)
	v_mfma_f32_32x32x16_bf16 v[48:63], v[224:227], v[240:243], v[48:63]
	v_mfma_f32_32x32x16_bf16 v[32:47], v[224:227], v[244:247], v[32:47]
	ds_read_b128 v[236:239], v101 offset:20480
	s_waitcnt lgkmcnt(4)
	v_mfma_f32_32x32x16_bf16 v[16:31], v[228:231], v[240:243], v[16:31]
	v_mfma_f32_32x32x16_bf16 v[0:15], v[228:231], v[244:247], v[0:15]
	s_waitcnt lgkmcnt(0)
	s_barrier
	v_mfma_f32_32x32x16_bf16 v[48:63], v[232:235], v[248:251], v[48:63]
	v_mfma_f32_32x32x16_bf16 v[32:47], v[232:235], v[252:255], v[32:47]
	v_mfma_f32_32x32x16_bf16 v[16:31], v[236:239], v[248:251], v[16:31]
	v_mfma_f32_32x32x16_bf16 v[0:15], v[236:239], v[252:255], v[0:15]
	s_setprio 0
	s_branch .LBB0_1409

; template <int EPI, int MI>
; DI void gemm_tile(const GemmDesc& g, int tm, int tn, char* smem) {
;     ...
;   const int tid = get_tid(), lane = tid & 63, wave = tid >> 6, r = lane & 31, hh = lane >> 5;
;   const int wm = wave >> 1, wn = wave & 1;
;   const int m0 = tm * BM, n0 = tn * 128;
;   const int nk = g.K >> 6;
;   f32x16 acc[MI][2];
; #pragma unroll
;   for (int a = 0; a < MI; ++a)
; #pragma unroll
;     for (int b = 0; b < 2; ++b)
; #pragma unroll
;       for (int i = 0; i < 16; ++i) acc[a][b][i] = 0.f;
;   const int srow = tid >> 3;
;   const int schunk = (tid & 7) ^ ((srow & 7) ^ ((srow >> 3) & 3));
;     ...
;   const int rowA = wm * (32 * MI) + r, rowB = wn * 64 + r;
;   const int hk = hh ^ ((r & 7) ^ ((r >> 3) & 3));
;     ...
;   G_GLDS(0, 0);
;   asm volatile("s_waitcnt vmcnt(0)" ::: "memory");
;   __syncthreads();
; template <int EPI, int MI>
; DI void gemm_phase(const GemmDesc& g, char* smem, int vb, int nvb) {
;     ...
;   for (int q = start; q < local; q += step) {
;     const int mg = q / per;
;     const int rem = q - mg * per;
;     const int tn = rem / PM;
;     const int tm = mbase + mg * PM + (rem - tn * PM);
.LBB0_1421:
	s_abs_i32 s1, s5
	v_readlane_b32 s15, v219, 45
	s_mul_hi_u32 s15, s1, s15
	v_readlane_b32 s18, v219, 44
	s_mul_i32 s16, s15, s18
	s_sub_i32 s1, s1, s16
	s_ashr_i32 s0, s5, 31
	s_add_i32 s16, s15, 1
	s_sub_i32 s17, s1, s18
	s_cmp_ge_u32 s1, s18
	s_cselect_b32 s15, s16, s15
	s_cselect_b32 s1, s17, s1
	s_add_i32 s16, s15, 1
	s_cmp_ge_u32 s1, s18
	s_cselect_b32 s1, s16, s15
	s_xor_b32 s1, s1, s0
	s_sub_i32 s15, s1, s0
	s_mul_i32 s16, s15, s18
	s_sub_i32 s16, s5, s16
	s_abs_i32 s18, s16
	v_readlane_b32 s19, v219, 46
	s_mul_hi_u32 s19, s18, s19
	v_readlane_b32 s40, v218, 32
	s_mul_i32 s38, s19, s40
	s_sub_i32 s18, s18, s38
	s_ashr_i32 s17, s16, 31
	s_add_i32 s38, s19, 1
	s_sub_i32 s39, s18, s40
	s_cmp_ge_u32 s18, s40
	s_cselect_b32 s19, s38, s19
	s_cselect_b32 s18, s39, s18
	s_add_i32 s38, s19, 1
	s_cmp_ge_u32 s18, s40
	s_cselect_b32 s18, s38, s19
	s_xor_b32 s18, s18, s17
	s_sub_i32 s39, s18, s17
	s_sub_i32 s15, s15, s39
	v_mov_b32_e32 v6, v132
	s_mul_i32 s15, s15, s40
	s_add_i32 s16, s16, s54
	s_add_i32 s38, s16, s15
	v_ashrrev_i32_e32 v97, 3, v6
	v_ashrrev_i32_e32 v120, 7, v6
	v_bfe_u32 v0, v6, 6, 2
	v_xor_b32_e32 v1, v97, v6
	s_mulk_i32 s38, 0xc0
	v_and_b32_e32 v121, 31, v6
	v_bitop3_b32 v2, v1, v0, 7 bitop3:0x6c
	v_mul_lo_u32 v0, v120, s6
	v_and_b32_e32 v115, 7, v6
	v_or_b32_e32 v8, v0, v121
	v_lshrrev_b32_e32 v0, 3, v6
	s_waitcnt vmcnt(10)
	v_add_u32_e32 v98, s38, v97
	v_bfe_u32 v122, v6, 5, 1
	v_bitop3_b32 v0, v0, v115, 3 bitop3:0x6c
	v_ashrrev_i32_e32 v99, 31, v98
	v_readlane_b32 s40, v223, 59
	v_xor_b32_e32 v9, v0, v122
	v_lshlrev_b64 v[0:1], 11, v[98:99]
	v_readlane_b32 s41, v223, 60
	v_lshlrev_b32_e32 v100, 4, v2
	v_lshl_add_u32 v2, s39, 7, v97
	v_lshlrev_b32_e32 v99, 4, v6
	v_lshl_add_u64 v[0:1], s[40:41], 0, v[0:1]
	v_ashrrev_i32_e32 v3, 31, v2
	v_readlane_b32 s40, v220, 54
	v_add_u32_e32 v124, 0, v99
	v_mov_b32_e32 v101, v96
	v_lshlrev_b64 v[2:3], 11, v[2:3]
	v_readlane_b32 s41, v220, 55
	v_readfirstlane_b32 s15, v124
	v_add_u32_e32 v125, 0x1000, v124
	v_lshl_add_u64 v[0:1], v[0:1], 0, v[100:101]
	v_lshl_add_u64 v[4:5], s[40:41], 0, v[2:3]
	s_mov_b32 m0, s15
	s_mov_b64 s[40:41], 0x10000
	v_readfirstlane_b32 s15, v125
	v_add_u32_e32 v126, 0x2000, v124
	v_bfe_u32 v123, v6, 6, 1
	global_load_lds_dwordx4 v[0:1], off
	v_lshl_add_u64 v[6:7], v[0:1], 0, s[40:41]
	s_mov_b32 m0, s15
	s_mov_b64 s[42:43], 0x20000
	v_readfirstlane_b32 s15, v126
	v_add_u32_e32 v127, 0x3000, v124
	global_load_lds_dwordx4 v[6:7], off
	v_lshl_add_u64 v[6:7], v[0:1], 0, s[42:43]
	s_mov_b32 m0, s15
	s_mov_b64 s[44:45], 0x30000
	v_readfirstlane_b32 s15, v127
	v_add_u32_e32 v128, 0x4000, v124
	global_load_lds_dwordx4 v[6:7], off
	v_lshl_add_u64 v[6:7], v[0:1], 0, s[44:45]
	s_mov_b32 m0, s15
	s_mov_b64 s[46:47], 0x40000
	v_readfirstlane_b32 s15, v128
	v_add_u32_e32 v129, 0x5000, v124
	global_load_lds_dwordx4 v[6:7], off
	v_lshl_add_u64 v[6:7], v[0:1], 0, s[46:47]
	s_mov_b32 m0, s15
	s_mov_b64 s[46:47], 0x50000
	v_readfirstlane_b32 s15, v129
	v_add_u32_e32 v130, 0xc000, v124
	global_load_lds_dwordx4 v[6:7], off
	v_lshl_add_u64 v[0:1], v[0:1], 0, s[46:47]
	s_mov_b32 m0, s15
	v_readfirstlane_b32 s15, v130
	v_add_u32_e32 v131, 0xd000, v124
	global_load_lds_dwordx4 v[0:1], off
	v_lshl_add_u64 v[0:1], v[4:5], 0, v[100:101]
	s_mov_b32 m0, s15
	v_readfirstlane_b32 s15, v131
	v_add_u32_e32 v153, 0xe000, v124
	global_load_lds_dwordx4 v[0:1], off
	v_lshl_add_u64 v[4:5], v[0:1], 0, s[40:41]
	s_mov_b32 m0, s15
	v_readfirstlane_b32 s15, v153
	v_add_u32_e32 v154, 0xf000, v124
	global_load_lds_dwordx4 v[4:5], off
	v_lshl_add_u64 v[4:5], v[0:1], 0, s[42:43]
	s_mov_b32 m0, s15
	v_readfirstlane_b32 s15, v154
	global_load_lds_dwordx4 v[4:5], off
	v_lshl_add_u64 v[0:1], v[0:1], 0, s[44:45]
	s_mov_b32 m0, s15
	s_mul_i32 s0, s0, 43
	global_load_lds_dwordx4 v[0:1], off
	s_add_i32 s17, s17, s0
	s_sub_i32 s0, s17, s18
	s_mul_i32 s1, s1, 43
	s_sub_i32 s0, s0, s1
	v_readlane_b32 s1, v218, 33
	v_lshlrev_b32_e32 v0, 7, v121
	s_mul_i32 s0, s1, s0
	v_lshl_or_b32 v0, v123, 13, v0
	s_add_i32 s0, s0, s4
	v_add_u32_e32 v156, 0, v0
	v_add_u32_e32 v158, s10, v0
	v_add_u32_e32 v0, s0, v97
	v_ashrrev_i32_e32 v1, 31, v0
	s_waitcnt vmcnt(0)
	v_lshlrev_b64 v[0:1], 11, v[0:1]
	v_lshlrev_b32_e32 v157, 4, v9
	s_waitcnt vmcnt(0)
	v_lshl_add_u64 v[102:103], s[70:71], 0, v[0:1]
	v_mov_b32_e32 v0, 0
	v_lshl_add_u32 v155, v8, 7, 0
	v_xor_b32_e32 v159, 32, v157
	v_xor_b32_e32 v160, 64, v157
	v_xor_b32_e32 v161, 0x60, v157
	v_lshl_add_u64 v[104:105], s[70:71], 0, v[2:3]
	s_mov_b32 s15, 0
	v_mov_b32_e32 v1, v0
	v_mov_b32_e32 v2, v0
	v_mov_b32_e32 v3, v0
	v_mov_b32_e32 v4, v0
	v_mov_b32_e32 v5, v0
	v_mov_b32_e32 v6, v0
	v_mov_b32_e32 v7, v0
	v_mov_b32_e32 v8, v0
	v_mov_b32_e32 v9, v0
	v_mov_b32_e32 v10, v0
	v_mov_b32_e32 v11, v0
	v_mov_b32_e32 v12, v0
	v_mov_b32_e32 v13, v0
	v_mov_b32_e32 v14, v0
	v_mov_b32_e32 v15, v0
	v_mov_b32_e32 v16, v0
	v_mov_b32_e32 v17, v0
	v_mov_b32_e32 v18, v0
	v_mov_b32_e32 v19, v0
	v_mov_b32_e32 v20, v0
	v_mov_b32_e32 v21, v0
	v_mov_b32_e32 v22, v0
	v_mov_b32_e32 v23, v0
	v_mov_b32_e32 v24, v0
	v_mov_b32_e32 v25, v0
	v_mov_b32_e32 v26, v0
	v_mov_b32_e32 v27, v0
	v_mov_b32_e32 v28, v0
	v_mov_b32_e32 v29, v0
	v_mov_b32_e32 v30, v0
	v_mov_b32_e32 v31, v0
	v_mov_b32_e32 v32, v0
	v_mov_b32_e32 v33, v0
	v_mov_b32_e32 v34, v0
	v_mov_b32_e32 v35, v0
	v_mov_b32_e32 v36, v0
	v_mov_b32_e32 v37, v0
	v_mov_b32_e32 v38, v0
	v_mov_b32_e32 v39, v0
	v_mov_b32_e32 v40, v0
	v_mov_b32_e32 v41, v0
	v_mov_b32_e32 v42, v0
	v_mov_b32_e32 v43, v0
	v_mov_b32_e32 v44, v0
	v_mov_b32_e32 v45, v0
	v_mov_b32_e32 v46, v0
	v_mov_b32_e32 v47, v0
	v_mov_b32_e32 v48, v0
	v_mov_b32_e32 v49, v0
	v_mov_b32_e32 v50, v0
	v_mov_b32_e32 v51, v0
	v_mov_b32_e32 v52, v0
	v_mov_b32_e32 v53, v0
	v_mov_b32_e32 v54, v0
	v_mov_b32_e32 v55, v0
	v_mov_b32_e32 v56, v0
	v_mov_b32_e32 v57, v0
	v_mov_b32_e32 v58, v0
	v_mov_b32_e32 v59, v0
	v_mov_b32_e32 v60, v0
	v_mov_b32_e32 v61, v0
	v_mov_b32_e32 v62, v0
	v_mov_b32_e32 v63, v0
	v_mov_b32_e32 v64, v0
	v_mov_b32_e32 v65, v0
	v_mov_b32_e32 v66, v0
	v_mov_b32_e32 v67, v0
	v_mov_b32_e32 v68, v0
	v_mov_b32_e32 v69, v0
	v_mov_b32_e32 v70, v0
	v_mov_b32_e32 v71, v0
	v_mov_b32_e32 v72, v0
	v_mov_b32_e32 v73, v0
	v_mov_b32_e32 v74, v0
	v_mov_b32_e32 v75, v0
	v_mov_b32_e32 v76, v0
	v_mov_b32_e32 v77, v0
	v_mov_b32_e32 v78, v0
	v_mov_b32_e32 v79, v0
	v_mov_b32_e32 v80, v0
	v_mov_b32_e32 v81, v0
	v_mov_b32_e32 v82, v0
	v_mov_b32_e32 v83, v0
	v_mov_b32_e32 v84, v0
	v_mov_b32_e32 v85, v0
	v_mov_b32_e32 v86, v0
	v_mov_b32_e32 v87, v0
	v_mov_b32_e32 v88, v0
	v_mov_b32_e32 v89, v0
	v_mov_b32_e32 v90, v0
	v_mov_b32_e32 v91, v0
	v_mov_b32_e32 v92, v0
	v_mov_b32_e32 v93, v0
	v_mov_b32_e32 v94, v0
	v_mov_b32_e32 v95, v0
	v_readlane_b32 s100, v218, 17
	s_nop 3
	s_cmp_lt_i32 s100, 0
	s_cbranch_scc0 .Lgb_noprio
	s_setprio 1
; template <int EPI, int MI>
; DI void gemm_tile(const GemmDesc& g, int tm, int tn, char* smem) {
;     ...
;   const int rowA = wm * (32 * MI) + r, rowB = wn * 64 + r;
;   const int hk = hh ^ ((r & 7) ^ ((r >> 3) & 3));
;     ...
;   G_GLDS(0, 0);
;   asm volatile("s_waitcnt vmcnt(0)" ::: "memory");
;   __syncthreads();
.Lgb_noprio:
	v_add_u32_e32 v162, v155, v157
	v_add_u32_e32 v163, v155, v159
	v_add_u32_e32 v164, v155, v160
	v_add_u32_e32 v165, v155, v161
	v_add_u32_e32 v166, v156, v157
	v_add_u32_e32 v167, v156, v159
	v_add_u32_e32 v168, v156, v160
	v_add_u32_e32 v169, v156, v161
	v_add_u32_e32 v170, v158, v157
	v_add_u32_e32 v171, v158, v159
	v_add_u32_e32 v172, v158, v160
	v_add_u32_e32 v173, v158, v161
	v_lshl_add_u64 v[252:253], v[102:103], 0, v[100:101]
	v_lshl_add_u64 v[254:255], v[104:105], 0, v[100:101]
	v_readfirstlane_b32 s100, v124
	s_mov_b64 s[0:1], 0x80
	s_waitcnt vmcnt(0) lgkmcnt(0)
	s_barrier
	s_add_u32 m0, s100, 0x6000
	v_lshl_add_u64 v[106:107], v[252:253], 0, s[96:97]
	global_load_lds_dwordx4 v[106:107], off
	s_add_u32 m0, s100, 0x7000
	v_lshl_add_u64 v[106:107], v[252:253], 0, s[50:51]
	global_load_lds_dwordx4 v[106:107], off
	ds_read_b128 v[236:239], v166 offset:49152
	ds_read_b128 v[240:243], v166 offset:53248
	ds_read_b128 v[224:227], v162
	ds_read_b128 v[228:231], v162 offset:4096
	s_mov_b32 s101, 0

; template <int EPI, int MI>
; DI void gemm_tile(const GemmDesc& g, int tm, int tn, char* smem) {
;     ...
;   const int tid = get_tid(), lane = tid & 63, wave = tid >> 6, r = lane & 31, hh = lane >> 5;
;   const int wm = wave >> 1, wn = wave & 1;
;   const int m0 = tm * BM, n0 = tn * 128;
;   const int nk = g.K >> 6;
;   f32x16 acc[MI][2];
; #pragma unroll
;   for (int a = 0; a < MI; ++a)
; #pragma unroll
;     for (int b = 0; b < 2; ++b)
; #pragma unroll
;       for (int i = 0; i < 16; ++i) acc[a][b][i] = 0.f;
;   const int srow = tid >> 3;
;   const int schunk = (tid & 7) ^ ((srow & 7) ^ ((srow >> 3) & 3));
;     ...
;   const int rowA = wm * (32 * MI) + r, rowB = wn * 64 + r;
;   const int hk = hh ^ ((r & 7) ^ ((r >> 3) & 3));
;     ...
;   G_GLDS(0, 0);
;   asm volatile("s_waitcnt vmcnt(0)" ::: "memory");
;   __syncthreads();
; template <int EPI, int MI>
; DI void gemm_phase(const GemmDesc& g, char* smem, int vb, int nvb) {
;     ...
;   for (int q = start; q < local; q += step) {
;     const int mg = q / per;
;     const int rem = q - mg * per;
;     const int tn = rem / PM;
;     const int tm = mbase + mg * PM + (rem - tn * PM);
.LBB0_1478:
	s_abs_i32 s0, s44
	s_mul_hi_u32 s1, s0, s42
	s_mul_i32 s4, s1, s38
	s_sub_i32 s0, s0, s4
	s_ashr_i32 s18, s44, 31
	s_add_i32 s4, s1, 1
	s_sub_i32 s5, s0, s38
	s_cmp_ge_u32 s0, s38
	s_cselect_b32 s1, s4, s1
	s_cselect_b32 s0, s5, s0
	s_add_i32 s4, s1, 1
	s_cmp_ge_u32 s0, s38
	s_cselect_b32 s0, s4, s1
	s_xor_b32 s19, s0, s18
	s_sub_i32 s0, s19, s18
	s_mul_i32 s1, s0, s38
	s_sub_i32 s1, s44, s1
	s_abs_i32 s4, s1
	s_mul_hi_u32 s5, s4, s16
	s_mul_i32 s45, s5, s15
	s_sub_i32 s4, s4, s45
	s_ashr_i32 s46, s1, 31
	s_add_i32 s45, s5, 1
	s_sub_i32 s47, s4, s15
	s_cmp_ge_u32 s4, s15
	s_cselect_b32 s5, s45, s5
	s_cselect_b32 s4, s47, s4
	s_add_i32 s45, s5, 1
	s_cmp_ge_u32 s4, s15
	s_cselect_b32 s4, s45, s5
	s_xor_b32 s47, s4, s46
	s_sub_i32 s4, s47, s46
	v_mov_b32_e32 v75, v132
	s_mul_i32 s0, s0, s15
	s_mul_i32 s5, s4, s15
	s_add_i32 s0, s0, s39
	v_ashrrev_i32_e32 v6, 3, v75
	s_sub_i32 s1, s1, s5
	v_bfe_u32 v1, v75, 6, 2
	v_xor_b32_e32 v2, v6, v75
	s_add_i32 s1, s0, s1
	s_lshl_b32 s0, s4, 7
	v_and_b32_e32 v0, 7, v75
	v_bitop3_b32 v2, v2, v1, 7 bitop3:0x6c
	v_lshrrev_b32_e32 v1, 3, v75
	v_readlane_b32 s4, v221, 5
	s_lshl_b32 s45, s1, 7
	v_bfe_u32 v77, v75, 5, 1
	v_bitop3_b32 v0, v1, v0, 3 bitop3:0x6c
	v_readlane_b32 s5, v221, 6
	v_xor_b32_e32 v7, v0, v77
	v_add_u32_e32 v3, s45, v6
	v_mov_b64_e32 v[0:1], s[4:5]
	s_movk_i32 s52, 0x1600
	v_mad_i64_i32 v[0:1], s[4:5], v3, s52, v[0:1]
	v_readlane_b32 s4, v220, 56
	v_readlane_b32 s5, v220, 57
	v_lshlrev_b32_e32 v64, 4, v2
	v_add_u32_e32 v8, s0, v6
	v_mov_b64_e32 v[2:3], s[4:5]
	v_lshlrev_b32_e32 v4, 4, v75
	v_mad_i64_i32 v[2:3], s[4:5], v8, s52, v[2:3]
	v_add_u32_e32 v78, 0, v4
	v_mov_b32_e32 v65, v96
	v_readfirstlane_b32 s4, v78
	v_add_u32_e32 v79, 0x1000, v78
	v_lshl_add_u64 v[0:1], v[0:1], 0, v[64:65]
	s_mov_b32 m0, s4
	s_mov_b64 s[72:73], 0x2c000
	v_readfirstlane_b32 s4, v79
	v_add_u32_e32 v80, 0x2000, v78
	global_load_lds_dwordx4 v[0:1], off
	v_lshl_add_u64 v[4:5], v[0:1], 0, s[72:73]
	s_mov_b32 m0, s4
	s_mov_b64 s[74:75], 0x58000
	v_readfirstlane_b32 s4, v80
	v_add_u32_e32 v81, 0x3000, v78
	global_load_lds_dwordx4 v[4:5], off
	v_lshl_add_u64 v[4:5], v[0:1], 0, s[74:75]
	s_mov_b32 m0, s4
	s_mov_b64 s[76:77], 0x84000
	v_readfirstlane_b32 s4, v81
	v_add_u32_e32 v82, 0x8000, v78
	global_load_lds_dwordx4 v[4:5], off
	v_lshl_add_u64 v[0:1], v[0:1], 0, s[76:77]
	s_mov_b32 m0, s4
	v_readfirstlane_b32 s4, v82
	v_add_u32_e32 v83, 0x9000, v78
	global_load_lds_dwordx4 v[0:1], off
	v_lshl_add_u64 v[0:1], v[2:3], 0, v[64:65]
	s_mov_b32 m0, s4
	v_readfirstlane_b32 s4, v83
	v_add_u32_e32 v84, 0xa000, v78
	global_load_lds_dwordx4 v[0:1], off
	v_lshl_add_u64 v[2:3], v[0:1], 0, s[72:73]
	s_mov_b32 m0, s4
	v_readfirstlane_b32 s4, v84
	v_add_u32_e32 v85, 0xb000, v78
	global_load_lds_dwordx4 v[2:3], off
	v_lshl_add_u64 v[2:3], v[0:1], 0, s[74:75]
	s_mov_b32 m0, s4
	v_readfirstlane_b32 s4, v85
	global_load_lds_dwordx4 v[2:3], off
	v_lshl_add_u64 v[0:1], v[0:1], 0, s[76:77]
	s_mov_b32 m0, s4
	s_mul_i32 s18, s18, 7
	global_load_lds_dwordx4 v[0:1], off
	v_and_b32_e32 v74, 31, v75
	s_add_i32 s46, s46, s18
	v_ashrrev_i32_e32 v76, 7, v75
	v_lshlrev_b32_e32 v0, 7, v74
	s_sub_i32 s4, s46, s47
	s_mul_i32 s19, s19, 7
	v_lshl_or_b32 v0, v76, 13, v0
	s_sub_i32 s4, s4, s19
	v_add_u32_e32 v86, 0, v0
	v_lshlrev_b32_e32 v0, 7, v75
	s_mul_i32 s4, s43, s4
	v_and_b32_e32 v0, 0x2f80, v0
	s_add_i32 s4, s4, s17
	s_waitcnt vmcnt(0)
	v_add_u32_e32 v87, 0, v0
	v_add_u32_e32 v2, s4, v6
	v_mov_b64_e32 v[0:1], s[70:71]
	s_waitcnt vmcnt(0)
	v_lshlrev_b32_e32 v88, 4, v7
	v_mad_i64_i32 v[66:67], s[4:5], v2, s52, v[0:1]
	v_mad_i64_i32 v[68:69], s[4:5], v8, s52, v[0:1]
	v_mov_b32_e32 v0, 0
	v_xor_b32_e32 v89, 32, v88
	v_xor_b32_e32 v90, 64, v88
	v_xor_b32_e32 v91, 0x60, v88
	s_mov_b32 s18, 0
	v_mov_b32_e32 v1, v0
	v_mov_b32_e32 v2, v0
	v_mov_b32_e32 v3, v0
	v_mov_b32_e32 v4, v0
	v_mov_b32_e32 v5, v0
	v_mov_b32_e32 v6, v0
	v_mov_b32_e32 v7, v0
	v_mov_b32_e32 v8, v0
	v_mov_b32_e32 v9, v0
	v_mov_b32_e32 v10, v0
	v_mov_b32_e32 v11, v0
	v_mov_b32_e32 v12, v0
	v_mov_b32_e32 v13, v0
	v_mov_b32_e32 v14, v0
	v_mov_b32_e32 v15, v0
	v_mov_b32_e32 v16, v0
	v_mov_b32_e32 v17, v0
	v_mov_b32_e32 v18, v0
	v_mov_b32_e32 v19, v0
	v_mov_b32_e32 v20, v0
	v_mov_b32_e32 v21, v0
	v_mov_b32_e32 v22, v0
	v_mov_b32_e32 v23, v0
	v_mov_b32_e32 v24, v0
	v_mov_b32_e32 v25, v0
	v_mov_b32_e32 v26, v0
	v_mov_b32_e32 v27, v0
	v_mov_b32_e32 v28, v0
	v_mov_b32_e32 v29, v0
	v_mov_b32_e32 v30, v0
	v_mov_b32_e32 v31, v0
	v_mov_b32_e32 v32, v0
	v_mov_b32_e32 v33, v0
	v_mov_b32_e32 v34, v0
	v_mov_b32_e32 v35, v0
	v_mov_b32_e32 v36, v0
	v_mov_b32_e32 v37, v0
	v_mov_b32_e32 v38, v0
	v_mov_b32_e32 v39, v0
	v_mov_b32_e32 v40, v0
	v_mov_b32_e32 v41, v0
	v_mov_b32_e32 v42, v0
	v_mov_b32_e32 v43, v0
	v_mov_b32_e32 v44, v0
	v_mov_b32_e32 v45, v0
	v_mov_b32_e32 v46, v0
	v_mov_b32_e32 v47, v0
	v_mov_b32_e32 v48, v0
	v_mov_b32_e32 v49, v0
	v_mov_b32_e32 v50, v0
	v_mov_b32_e32 v51, v0
	v_mov_b32_e32 v52, v0
	v_mov_b32_e32 v53, v0
	v_mov_b32_e32 v54, v0
	v_mov_b32_e32 v55, v0
	v_mov_b32_e32 v56, v0
	v_mov_b32_e32 v57, v0
	v_mov_b32_e32 v58, v0
	v_mov_b32_e32 v59, v0
	v_mov_b32_e32 v60, v0
	v_mov_b32_e32 v61, v0
	v_mov_b32_e32 v62, v0
	v_mov_b32_e32 v63, v0
	v_readlane_b32 s100, v218, 17
	s_nop 3
	s_cmp_lt_i32 s100, 0
	s_cbranch_scc0 .Lgf_noprio
	s_setprio 1
.Lgf_noprio:
	v_add_u32_e32 v92, v86, v88
	v_add_u32_e32 v93, v86, v89
	v_add_u32_e32 v94, v86, v90
	v_add_u32_e32 v95, v86, v91
	v_add_u32_e32 v97, v87, v88
	v_add_u32_e32 v98, v87, v89
	v_add_u32_e32 v99, v87, v90
	v_add_u32_e32 v100, v87, v91
	v_lshl_add_u64 v[104:105], v[66:67], 0, v[64:65]
	v_lshl_add_u64 v[106:107], v[68:69], 0, v[64:65]
	v_readfirstlane_b32 s100, v78
	s_mov_b64 s[46:47], 0x80
	s_waitcnt vmcnt(0) lgkmcnt(0)
	s_barrier
	s_mov_b64 s[4:5], 0x5872080
	s_add_u32 m0, s100, 0x4000
	v_lshl_add_u64 v[102:103], v[104:105], 0, s[4:5]
	global_load_lds_dwordx4 v[102:103], off
	s_mov_b64 s[4:5], 0x589e080
	s_add_u32 m0, s100, 0x5000
	v_lshl_add_u64 v[102:103], v[104:105], 0, s[4:5]
	global_load_lds_dwordx4 v[102:103], off
	ds_read_b128 v[240:243], v97 offset:32768
	ds_read_b128 v[244:247], v97 offset:36864
	ds_read_b128 v[224:227], v92
	ds_read_b128 v[228:231], v92 offset:4096
	s_mov_b32 s101, 0

; template <int EPI, int MI>
; DI void gemm_tile(const GemmDesc& g, int tm, int tn, char* smem) {
;     ...
;   for (int kt = 0; kt < nk; kt += 2) {
;     if (kt + 1 < nk) G_GLDS(kt + 1, 1);
;     G_COMPUTE(0);
;     asm volatile("s_waitcnt vmcnt(0)" ::: "memory");
;     __syncthreads();
;     if (kt + 1 < nk) {
;       if (kt + 2 < nk) G_GLDS(kt + 2, 0);
;       G_COMPUTE(1);
;       asm volatile("s_waitcnt vmcnt(0)" ::: "memory");
;       __syncthreads();
;     }
;   }
.Lgf_last:
	ds_read_b128 v[248:251], v98 offset:49152
	ds_read_b128 v[252:255], v98 offset:53248
	ds_read_b128 v[232:235], v93 offset:16384
	s_waitcnt lgkmcnt(4)
	v_mfma_f32_32x32x16_bf16 v[48:63], v[224:227], v[240:243], v[48:63]
	v_mfma_f32_32x32x16_bf16 v[32:47], v[224:227], v[244:247], v[32:47]
	ds_read_b128 v[236:239], v93 offset:20480
	s_waitcnt lgkmcnt(4)
	v_mfma_f32_32x32x16_bf16 v[16:31], v[228:231], v[240:243], v[16:31]
	v_mfma_f32_32x32x16_bf16 v[0:15], v[228:231], v[244:247], v[0:15]
	ds_read_b128 v[240:243], v99 offset:49152
	ds_read_b128 v[244:247], v99 offset:53248
	ds_read_b128 v[224:227], v94 offset:16384
	s_waitcnt lgkmcnt(4)
	v_mfma_f32_32x32x16_bf16 v[48:63], v[232:235], v[248:251], v[48:63]
	v_mfma_f32_32x32x16_bf16 v[32:47], v[232:235], v[252:255], v[32:47]
	ds_read_b128 v[228:231], v94 offset:20480
	s_waitcnt lgkmcnt(4)
	v_mfma_f32_32x32x16_bf16 v[16:31], v[236:239], v[248:251], v[16:31]
	v_mfma_f32_32x32x16_bf16 v[0:15], v[236:239], v[252:255], v[0:15]
	ds_read_b128 v[248:251], v100 offset:49152
	ds_read_b128 v[252:255], v100 offset:53248
	ds_read_b128 v[232:235], v95 offset:16384
	s_waitcnt lgkmcnt(4)
	v_mfma_f32_32x32x16_bf16 v[48:63], v[224:227], v[240:243], v[48:63]
	v_mfma_f32_32x32x16_bf16 v[32:47], v[224:227], v[244:247], v[32:47]
	ds_read_b128 v[236:239], v95 offset:20480
	s_waitcnt lgkmcnt(4)
	v_mfma_f32_32x32x16_bf16 v[16:31], v[228:231], v[240:243], v[16:31]
	v_mfma_f32_32x32x16_bf16 v[0:15], v[228:231], v[244:247], v[0:15]
	s_waitcnt lgkmcnt(0)
	s_barrier
	v_mfma_f32_32x32x16_bf16 v[48:63], v[232:235], v[248:251], v[48:63]
	v_mfma_f32_32x32x16_bf16 v[32:47], v[232:235], v[252:255], v[32:47]
	v_mfma_f32_32x32x16_bf16 v[16:31], v[236:239], v[248:251], v[16:31]
	v_mfma_f32_32x32x16_bf16 v[0:15], v[236:239], v[252:255], v[0:15]
	s_setprio 0
	s_branch .LBB0_1482

; template <int EPI, int MI>
; DI void gemm_tile(const GemmDesc& g, int tm, int tn, char* smem) {
;     ...
;   const int tid = get_tid(), lane = tid & 63, wave = tid >> 6, r = lane & 31, hh = lane >> 5;
;   const int wm = wave >> 1, wn = wave & 1;
;   const int m0 = tm * BM, n0 = tn * 128;
;   const int nk = g.K >> 6;
;   f32x16 acc[MI][2];
; #pragma unroll
;   for (int a = 0; a < MI; ++a)
; #pragma unroll
;     for (int b = 0; b < 2; ++b)
; #pragma unroll
;       for (int i = 0; i < 16; ++i) acc[a][b][i] = 0.f;
;   const int srow = tid >> 3;
;   const int schunk = (tid & 7) ^ ((srow & 7) ^ ((srow >> 3) & 3));
;     ...
;   const int rowA = wm * (32 * MI) + r, rowB = wn * 64 + r;
;   const int hk = hh ^ ((r & 7) ^ ((r >> 3) & 3));
;     ...
;   G_GLDS(0, 0);
;   asm volatile("s_waitcnt vmcnt(0)" ::: "memory");
;   __syncthreads();
; template <int EPI, int MI>
; DI void gemm_phase(const GemmDesc& g, char* smem, int vb, int nvb) {
;     ...
;   for (int q = start; q < local; q += step) {
;     const int mg = q / per;
;     const int rem = q - mg * per;
;     const int tn = rem / PM;
;     const int tm = mbase + mg * PM + (rem - tn * PM);
.LBB0_1491:
	s_abs_i32 s0, s40
	v_readlane_b32 s1, v219, 48
	s_mul_hi_u32 s1, s0, s1
	v_readlane_b32 s17, v219, 47
	s_mul_i32 s4, s1, s17
	s_sub_i32 s0, s0, s4
	s_ashr_i32 s15, s40, 31
	s_add_i32 s4, s1, 1
	s_sub_i32 s5, s0, s17
	s_cmp_ge_u32 s0, s17
	s_cselect_b32 s1, s4, s1
	s_cselect_b32 s0, s5, s0
	s_add_i32 s4, s1, 1
	s_cmp_ge_u32 s0, s17
	s_cselect_b32 s0, s4, s1
	s_xor_b32 s16, s0, s15
	s_sub_i32 s0, s16, s15
	s_mul_i32 s1, s0, s17
	s_sub_i32 s1, s40, s1
	s_abs_i32 s4, s1
	v_readlane_b32 s5, v219, 46
	s_mul_hi_u32 s5, s4, s5
	v_readlane_b32 s41, v218, 32
	s_mul_i32 s18, s5, s41
	s_sub_i32 s4, s4, s18
	s_ashr_i32 s17, s1, 31
	s_add_i32 s18, s5, 1
	s_sub_i32 s19, s4, s41
	s_cmp_ge_u32 s4, s41
	s_cselect_b32 s5, s18, s5
	s_cselect_b32 s4, s19, s4
	s_add_i32 s18, s5, 1
	s_cmp_ge_u32 s4, s41
	s_cselect_b32 s4, s18, s5
	s_xor_b32 s18, s4, s17
	v_mov_b32_e32 v97, v132
	s_sub_i32 s4, s18, s17
	s_mul_i32 s0, s0, s41
	v_ashrrev_i32_e32 v6, 3, v97
	s_mul_i32 s5, s4, s41
	s_waitcnt vmcnt(8)
	v_ashrrev_i32_e32 v109, 7, v97
	v_bfe_u32 v1, v97, 6, 2
	v_xor_b32_e32 v2, v6, v97
	s_add_i32 s0, s0, s54
	s_sub_i32 s1, s1, s5
	v_and_b32_e32 v108, 31, v97
	v_bitop3_b32 v2, v2, v1, 7 bitop3:0x6c
	v_mul_lo_u32 v1, v109, s6
	s_add_i32 s1, s0, s1
	s_lshl_b32 s0, s4, 7
	v_and_b32_e32 v0, 7, v97
	v_or_b32_e32 v7, v1, v108
	v_lshrrev_b32_e32 v1, 3, v97
	v_readlane_b32 s4, v221, 5
	s_mul_i32 s41, s1, 0xc0
	v_bfe_u32 v115, v97, 5, 1
	v_bitop3_b32 v0, v1, v0, 3 bitop3:0x6c
	v_readlane_b32 s5, v221, 6
	v_xor_b32_e32 v8, v0, v115
	v_add_u32_e32 v3, s41, v6
	v_mov_b64_e32 v[0:1], s[4:5]
	s_movk_i32 s19, 0x1600
	v_mad_i64_i32 v[0:1], s[4:5], v3, s19, v[0:1]
	v_readlane_b32 s4, v220, 56
	v_readlane_b32 s5, v220, 57
	v_lshlrev_b32_e32 v98, 4, v2
	v_add_u32_e32 v9, s0, v6
	v_mov_b64_e32 v[2:3], s[4:5]
	v_lshlrev_b32_e32 v120, 4, v97
	v_mad_i64_i32 v[2:3], s[4:5], v9, s19, v[2:3]
	v_add_u32_e32 v121, 0, v120
	v_mov_b32_e32 v99, v96
	v_readfirstlane_b32 s4, v121
	v_add_u32_e32 v122, 0x1000, v121
	v_lshl_add_u64 v[0:1], v[0:1], 0, v[98:99]
	s_mov_b32 m0, s4
	s_mov_b64 s[42:43], 0x2c000
	v_readfirstlane_b32 s4, v122
	v_add_u32_e32 v123, 0x2000, v121
	global_load_lds_dwordx4 v[0:1], off
	v_lshl_add_u64 v[4:5], v[0:1], 0, s[42:43]
	s_mov_b32 m0, s4
	s_mov_b64 s[44:45], 0x58000
	v_readfirstlane_b32 s4, v123
	v_add_u32_e32 v124, 0x3000, v121
	global_load_lds_dwordx4 v[4:5], off
	v_lshl_add_u64 v[4:5], v[0:1], 0, s[44:45]
	s_mov_b32 m0, s4
	s_mov_b64 s[46:47], 0x84000
	v_readfirstlane_b32 s4, v124
	global_load_lds_dwordx4 v[4:5], off
	v_lshl_add_u64 v[4:5], v[0:1], 0, s[46:47]
	s_mov_b32 m0, s4
	s_mov_b64 s[4:5], 0xb0000
	v_add_u32_e32 v125, 0x4000, v121
	global_load_lds_dwordx4 v[4:5], off
	v_lshl_add_u64 v[4:5], v[0:1], 0, s[4:5]
	v_readfirstlane_b32 s4, v125
	s_mov_b32 m0, s4
	s_mov_b64 s[4:5], 0xdc000
	v_add_u32_e32 v126, 0x5000, v121
	v_lshl_add_u64 v[0:1], v[0:1], 0, s[4:5]
	v_readfirstlane_b32 s4, v126
	v_add_u32_e32 v127, 0xc000, v121
	global_load_lds_dwordx4 v[4:5], off
	s_mov_b32 m0, s4
	v_readfirstlane_b32 s4, v127
	v_add_u32_e32 v128, 0xd000, v121
	global_load_lds_dwordx4 v[0:1], off
	v_lshl_add_u64 v[0:1], v[2:3], 0, v[98:99]
	s_mov_b32 m0, s4
	v_readfirstlane_b32 s4, v128
	v_add_u32_e32 v129, 0xe000, v121
	global_load_lds_dwordx4 v[0:1], off
	v_lshl_add_u64 v[2:3], v[0:1], 0, s[42:43]
	s_mov_b32 m0, s4
	v_readfirstlane_b32 s4, v129
	v_add_u32_e32 v130, 0xf000, v121
	global_load_lds_dwordx4 v[2:3], off
	v_lshl_add_u64 v[2:3], v[0:1], 0, s[44:45]
	s_mov_b32 m0, s4
	v_readfirstlane_b32 s4, v130
	global_load_lds_dwordx4 v[2:3], off
	v_lshl_add_u64 v[0:1], v[0:1], 0, s[46:47]
	s_mov_b32 m0, s4
	s_mul_i32 s15, s15, 7
	global_load_lds_dwordx4 v[0:1], off
	s_add_i32 s17, s17, s15
	s_sub_i32 s4, s17, s18
	s_mul_i32 s16, s16, 7
	s_sub_i32 s4, s4, s16
	v_readlane_b32 s5, v218, 33
	v_lshlrev_b32_e32 v0, 7, v97
	s_mul_i32 s4, s5, s4
	v_and_b32_e32 v0, 0x2f80, v0
	s_add_i32 s4, s4, s39
	s_waitcnt vmcnt(0)
	v_add_u32_e32 v153, 0, v0
	v_add_u32_e32 v155, s10, v0
	v_add_u32_e32 v2, s4, v6
	v_mov_b64_e32 v[0:1], s[70:71]
	v_lshlrev_b32_e32 v154, 4, v8
	v_mad_i64_i32 v[100:101], s[4:5], v2, s19, v[0:1]
	v_mad_i64_i32 v[102:103], s[4:5], v9, s19, v[0:1]
	v_mov_b32_e32 v0, 0
	v_lshl_add_u32 v131, v7, 7, 0
	v_xor_b32_e32 v156, 32, v154
	v_xor_b32_e32 v157, 64, v154
	v_xor_b32_e32 v158, 0x60, v154
	s_mov_b32 s15, 0
	v_mov_b32_e32 v1, v0
	v_mov_b32_e32 v2, v0
	v_mov_b32_e32 v3, v0
	v_mov_b32_e32 v4, v0
	v_mov_b32_e32 v5, v0
	v_mov_b32_e32 v6, v0
	v_mov_b32_e32 v7, v0
	v_mov_b32_e32 v8, v0
	v_mov_b32_e32 v9, v0
	v_mov_b32_e32 v10, v0
	v_mov_b32_e32 v11, v0
	v_mov_b32_e32 v12, v0
	v_mov_b32_e32 v13, v0
	v_mov_b32_e32 v14, v0
	v_mov_b32_e32 v15, v0
	v_mov_b32_e32 v16, v0
	v_mov_b32_e32 v17, v0
	v_mov_b32_e32 v18, v0
	v_mov_b32_e32 v19, v0
	v_mov_b32_e32 v20, v0
	v_mov_b32_e32 v21, v0
	v_mov_b32_e32 v22, v0
	v_mov_b32_e32 v23, v0
	v_mov_b32_e32 v24, v0
	v_mov_b32_e32 v25, v0
	v_mov_b32_e32 v26, v0
	v_mov_b32_e32 v27, v0
	v_mov_b32_e32 v28, v0
	v_mov_b32_e32 v29, v0
	v_mov_b32_e32 v30, v0
	v_mov_b32_e32 v31, v0
	v_mov_b32_e32 v32, v0
	v_mov_b32_e32 v33, v0
	v_mov_b32_e32 v34, v0
	v_mov_b32_e32 v35, v0
	v_mov_b32_e32 v36, v0
	v_mov_b32_e32 v37, v0
	v_mov_b32_e32 v38, v0
	v_mov_b32_e32 v39, v0
	v_mov_b32_e32 v40, v0
	v_mov_b32_e32 v41, v0
	v_mov_b32_e32 v42, v0
	v_mov_b32_e32 v43, v0
	v_mov_b32_e32 v44, v0
	v_mov_b32_e32 v45, v0
	v_mov_b32_e32 v46, v0
	v_mov_b32_e32 v47, v0
	v_mov_b32_e32 v48, v0
	s_waitcnt vmcnt(0)
	v_mov_b32_e32 v49, v0
	v_mov_b32_e32 v50, v0
	v_mov_b32_e32 v51, v0
	v_mov_b32_e32 v52, v0
	v_mov_b32_e32 v53, v0
	v_mov_b32_e32 v54, v0
	v_mov_b32_e32 v55, v0
	v_mov_b32_e32 v56, v0
	v_mov_b32_e32 v57, v0
	v_mov_b32_e32 v58, v0
	v_mov_b32_e32 v59, v0
	v_mov_b32_e32 v60, v0
	v_mov_b32_e32 v61, v0
	v_mov_b32_e32 v62, v0
	v_mov_b32_e32 v63, v0
	v_mov_b32_e32 v64, v0
	v_mov_b32_e32 v65, v0
	v_mov_b32_e32 v66, v0
	v_mov_b32_e32 v67, v0
	v_mov_b32_e32 v68, v0
	v_mov_b32_e32 v69, v0
	v_mov_b32_e32 v70, v0
	v_mov_b32_e32 v71, v0
	v_mov_b32_e32 v72, v0
	v_mov_b32_e32 v73, v0
	v_mov_b32_e32 v74, v0
	v_mov_b32_e32 v75, v0
	v_mov_b32_e32 v76, v0
	v_mov_b32_e32 v77, v0
	v_mov_b32_e32 v78, v0
	v_mov_b32_e32 v79, v0
	v_mov_b32_e32 v80, v0
	v_mov_b32_e32 v81, v0
	v_mov_b32_e32 v82, v0
	v_mov_b32_e32 v83, v0
	v_mov_b32_e32 v84, v0
	v_mov_b32_e32 v85, v0
	v_mov_b32_e32 v86, v0
	v_mov_b32_e32 v87, v0
	v_mov_b32_e32 v88, v0
	v_mov_b32_e32 v89, v0
	v_mov_b32_e32 v90, v0
	v_mov_b32_e32 v91, v0
	v_mov_b32_e32 v92, v0
	v_mov_b32_e32 v93, v0
	v_mov_b32_e32 v94, v0
	v_mov_b32_e32 v95, v0
	v_readlane_b32 s100, v218, 17
	s_nop 3
	s_cmp_lt_i32 s100, 0
	s_cbranch_scc0 .Lge_noprio
	s_setprio 1
